# snake MFMA order plus first-K-iteration peel (no accumulator zeroing)
# speedup vs baseline: 1.0019x; 1.0019x over previous
.LBB0_258:
	s_mov_b32 s24, s21
	s_mov_b32 s20, s25
	s_ashr_i32 s25, s21, 31
	s_xor_b64 s[60:61], s[26:27], -1
	s_lshl_b64 s[12:13], s[24:25], 20
	s_add_u32 s12, s18, s12
	s_addc_u32 s13, s19, s13
	s_cmp_gt_i32 s33, 0
	s_cselect_b32 s14, 0x80000, 0
	s_add_u32 s48, s12, s14
	s_addc_u32 s49, s13, 0
	s_and_b64 s[12:13], s[36:37], exec
	s_mov_b32 s71, s33
	s_cselect_b32 s25, s49, s59
	s_cselect_b32 s33, s48, s58
	s_ashr_i32 s21, s20, 31
	s_lshl_b64 s[12:13], s[20:21], 20
	s_add_u32 s54, s22, s12
	s_addc_u32 s55, s23, s13
	s_and_b64 s[12:13], s[36:37], exec
	s_cselect_b32 s21, s55, s51
	s_cselect_b32 s73, s54, s50
	s_cmp_gt_i32 s71, -1
	s_cselect_b64 s[56:57], -1, 0
	s_add_u32 s12, s58, 0x80
	v_cndmask_b32_e64 v2, 0, 1, s[56:57]
	v_cndmask_b32_e64 v8, 0, 1, s[26:27]
	s_addc_u32 s13, s59, 0
	v_cndmask_b32_e64 v2, v8, v2, s[36:37]
	v_lshl_add_u64 v[8:9], s[12:13], 0, v[214:215]
	v_and_b32_e32 v2, 1, v2
	v_lshl_add_u64 v[220:221], v[8:9], 0, v[218:219]
	v_lshl_add_u64 v[8:9], s[12:13], 0, v[216:217]
	v_cmp_eq_u32_e32 vcc, 1, v2
	v_lshl_add_u64 v[222:223], v[8:9], 0, v[218:219]
	s_add_u32 s26, s50, 0x100
	v_cndmask_b32_e64 v2, v246, 0, vcc
	s_addc_u32 s27, s51, 0
	s_mov_b32 s74, -2
	s_mov_b64 s[62:63], 0
	v_add_u32_e32 v168, 0x10000, v232
	v_add_u32_e32 v180, 0x14000, v232
	v_lshl_add_u64 v[224:225], v[222:223], 0, s[62:63]
	s_add_i32 m0, s35, 0xc000
	s_waitcnt lgkmcnt(0)
	ds_read_b128 v[148:151], v207
	ds_read_b128 v[164:167], v207 offset:1024
	ds_read_b128 v[144:147], v207 offset:2048
	ds_read_b128 v[160:163], v207 offset:3072
	ds_read_b128 v[140:143], v207 offset:4096
	ds_read_b128 v[156:159], v207 offset:5120
	ds_read_b128 v[136:139], v207 offset:6144
	ds_read_b128 v[152:155], v207 offset:7168
	ds_read_b128 v[184:187], v168
	ds_read_b128 v[188:191], v168 offset:1024
	ds_read_b128 v[192:195], v168 offset:2048
	ds_read_b128 v[196:199], v168 offset:3072
	ds_read_b128 v[168:171], v180
	ds_read_b128 v[172:175], v180 offset:1024
	ds_read_b128 v[176:179], v180 offset:2048
	ds_read_b128 v[180:183], v180 offset:3072
	global_load_lds_dwordx4 v[224:225], off
	v_lshl_add_u64 v[224:225], v[220:221], 0, s[62:63]
	s_add_i32 m0, s35, 0xe000
	s_nop 0
	global_load_lds_dwordx4 v[224:225], off
	s_waitcnt vmcnt(8)
	s_waitcnt lgkmcnt(0)
	s_barrier
	s_waitcnt lgkmcnt(0)
	v_mfma_f32_16x16x32_bf16 v[132:135], v[184:187], v[148:151], 0
	v_mfma_f32_16x16x32_bf16 v[132:135], v[188:191], v[164:167], v[132:135]
	v_mfma_f32_16x16x32_bf16 v[128:131], v[192:195], v[148:151], 0
	v_mfma_f32_16x16x32_bf16 v[128:131], v[196:199], v[164:167], v[128:131]
	v_mfma_f32_16x16x32_bf16 v[124:127], v[168:171], v[148:151], 0
	v_mfma_f32_16x16x32_bf16 v[124:127], v[172:175], v[164:167], v[124:127]
	v_mfma_f32_16x16x32_bf16 v[120:123], v[176:179], v[148:151], 0
	v_mfma_f32_16x16x32_bf16 v[120:123], v[180:183], v[164:167], v[120:123]
	v_mfma_f32_16x16x32_bf16 v[104:107], v[176:179], v[144:147], 0
	v_mfma_f32_16x16x32_bf16 v[104:107], v[180:183], v[160:163], v[104:107]
	v_mfma_f32_16x16x32_bf16 v[108:111], v[168:171], v[144:147], 0
	v_mfma_f32_16x16x32_bf16 v[108:111], v[172:175], v[160:163], v[108:111]
	v_mfma_f32_16x16x32_bf16 v[112:115], v[192:195], v[144:147], 0
	v_mfma_f32_16x16x32_bf16 v[112:115], v[196:199], v[160:163], v[112:115]
	v_mfma_f32_16x16x32_bf16 v[116:119], v[184:187], v[144:147], 0
	v_mfma_f32_16x16x32_bf16 v[116:119], v[188:191], v[160:163], v[116:119]
	v_mfma_f32_16x16x32_bf16 v[100:103], v[184:187], v[140:143], 0
	v_mfma_f32_16x16x32_bf16 v[100:103], v[188:191], v[156:159], v[100:103]
	v_mfma_f32_16x16x32_bf16 v[96:99], v[192:195], v[140:143], 0
	v_mfma_f32_16x16x32_bf16 v[96:99], v[196:199], v[156:159], v[96:99]
	v_mfma_f32_16x16x32_bf16 v[92:95], v[168:171], v[140:143], 0
	v_mfma_f32_16x16x32_bf16 v[92:95], v[172:175], v[156:159], v[92:95]
	v_mfma_f32_16x16x32_bf16 v[88:91], v[176:179], v[140:143], 0
	v_mfma_f32_16x16x32_bf16 v[88:91], v[180:183], v[156:159], v[88:91]
	v_mfma_f32_16x16x32_bf16 v[72:75], v[176:179], v[136:139], 0
	v_mfma_f32_16x16x32_bf16 v[72:75], v[180:183], v[152:155], v[72:75]
	v_mfma_f32_16x16x32_bf16 v[76:79], v[168:171], v[136:139], 0
	v_mfma_f32_16x16x32_bf16 v[76:79], v[172:175], v[152:155], v[76:79]
	v_mfma_f32_16x16x32_bf16 v[80:83], v[192:195], v[136:139], 0
	v_mfma_f32_16x16x32_bf16 v[80:83], v[196:199], v[152:155], v[80:83]
	v_mfma_f32_16x16x32_bf16 v[84:87], v[184:187], v[136:139], 0
	v_mfma_f32_16x16x32_bf16 v[84:87], v[188:191], v[152:155], v[84:87]
	s_barrier
	v_cndmask_b32_e64 v204, 0, 1, s[60:61]
	v_cmp_ne_u32_e64 s[50:51], 1, v204
	s_andn2_b64 vcc, exec, s[60:61]
	s_cbranch_vccnz .Lpeel0_262
	ds_read_b128 v[148:151], v207 offset:16384
	ds_read_b128 v[164:167], v207 offset:17408
	ds_read_b128 v[144:147], v207 offset:18432
	ds_read_b128 v[160:163], v207 offset:19456
	ds_read_b128 v[140:143], v207 offset:20480
	ds_read_b128 v[156:159], v207 offset:21504
	ds_read_b128 v[136:139], v207 offset:22528
	ds_read_b128 v[152:155], v207 offset:23552
.Lpeel0_262:
	s_add_u32 s12, s58, s62
	s_addc_u32 s13, s59, s63
	s_add_u32 s14, s12, 0x100
	s_addc_u32 s15, s13, 0
	s_add_u32 s75, s26, s62
	s_addc_u32 s76, s27, s63
	s_cmpk_eq_i32 s62, 0xf00
	s_cselect_b64 s[52:53], -1, 0
	s_and_b64 s[12:13], s[52:53], exec
	s_cselect_b32 s13, s21, s76
	s_cselect_b32 s12, s73, s75
	s_mov_b32 m0, s38
	s_cselect_b32 s15, s25, s15
	s_cselect_b32 s14, s33, s14
	v_lshl_add_u64 v[224:225], s[12:13], 0, v[208:209]
	s_add_u32 s76, s12, 0x80000
	global_load_lds_dwordx4 v[224:225], off
	v_lshl_add_u64 v[226:227], s[12:13], 0, v[212:213]
	s_mov_b32 m0, s39
	s_addc_u32 s77, s13, 0
	global_load_lds_dwordx4 v[226:227], off
	v_lshl_add_u64 v[228:229], s[76:77], 0, v[208:209]
	s_mov_b32 m0, s40
	v_lshl_add_u64 v[230:231], s[14:15], 0, v[210:211]
	global_load_lds_dwordx4 v[228:229], off
	v_lshl_add_u64 v[228:229], s[76:77], 0, v[212:213]
	s_mov_b32 m0, s41
	s_and_b64 vcc, exec, s[50:51]
	global_load_lds_dwordx4 v[228:229], off
	v_lshl_add_u64 v[228:229], s[14:15], 0, v[4:5]
	s_mov_b32 m0, s35
	s_nop 0
	global_load_lds_dwordx4 v[228:229], off
	s_mov_b32 m0, s43
	s_nop 0
	global_load_lds_dwordx4 v[230:231], off
	s_waitcnt vmcnt(8)
	s_waitcnt lgkmcnt(0)
	s_barrier
	s_cbranch_vccnz .Lpeel0_264
	s_waitcnt lgkmcnt(0)
	v_mfma_f32_16x16x32_bf16 v[68:71], v[184:187], v[148:151], 0
	v_mfma_f32_16x16x32_bf16 v[68:71], v[188:191], v[164:167], v[68:71]
	v_mfma_f32_16x16x32_bf16 v[64:67], v[192:195], v[148:151], 0
	v_mfma_f32_16x16x32_bf16 v[64:67], v[196:199], v[164:167], v[64:67]
	v_mfma_f32_16x16x32_bf16 v[60:63], v[168:171], v[148:151], 0
	v_mfma_f32_16x16x32_bf16 v[60:63], v[172:175], v[164:167], v[60:63]
	v_mfma_f32_16x16x32_bf16 v[56:59], v[176:179], v[148:151], 0
	v_mfma_f32_16x16x32_bf16 v[56:59], v[180:183], v[164:167], v[56:59]
	v_mfma_f32_16x16x32_bf16 v[40:43], v[176:179], v[144:147], 0
	v_mfma_f32_16x16x32_bf16 v[40:43], v[180:183], v[160:163], v[40:43]
	v_mfma_f32_16x16x32_bf16 v[44:47], v[168:171], v[144:147], 0
	v_mfma_f32_16x16x32_bf16 v[44:47], v[172:175], v[160:163], v[44:47]
	v_mfma_f32_16x16x32_bf16 v[48:51], v[192:195], v[144:147], 0
	v_mfma_f32_16x16x32_bf16 v[48:51], v[196:199], v[160:163], v[48:51]
	v_mfma_f32_16x16x32_bf16 v[52:55], v[184:187], v[144:147], 0
	v_mfma_f32_16x16x32_bf16 v[52:55], v[188:191], v[160:163], v[52:55]
	v_mfma_f32_16x16x32_bf16 v[36:39], v[184:187], v[140:143], 0
	v_mfma_f32_16x16x32_bf16 v[36:39], v[188:191], v[156:159], v[36:39]
	v_mfma_f32_16x16x32_bf16 v[32:35], v[192:195], v[140:143], 0
	v_mfma_f32_16x16x32_bf16 v[32:35], v[196:199], v[156:159], v[32:35]
	v_mfma_f32_16x16x32_bf16 v[28:31], v[168:171], v[140:143], 0
	v_mfma_f32_16x16x32_bf16 v[28:31], v[172:175], v[156:159], v[28:31]
	v_mfma_f32_16x16x32_bf16 v[24:27], v[176:179], v[140:143], 0
	v_mfma_f32_16x16x32_bf16 v[24:27], v[180:183], v[156:159], v[24:27]
	v_mfma_f32_16x16x32_bf16 v[8:11], v[176:179], v[136:139], 0
	v_mfma_f32_16x16x32_bf16 v[8:11], v[180:183], v[152:155], v[8:11]
	v_mfma_f32_16x16x32_bf16 v[12:15], v[168:171], v[136:139], 0
	v_mfma_f32_16x16x32_bf16 v[12:15], v[172:175], v[152:155], v[12:15]
	v_mfma_f32_16x16x32_bf16 v[16:19], v[192:195], v[136:139], 0
	v_mfma_f32_16x16x32_bf16 v[16:19], v[196:199], v[152:155], v[16:19]
	v_mfma_f32_16x16x32_bf16 v[20:23], v[184:187], v[136:139], 0
	v_mfma_f32_16x16x32_bf16 v[20:23], v[188:191], v[152:155], v[20:23]

.Lpeel0_266:
	s_mov_b32 m0, s64
	v_lshl_add_u64 v[224:225], v[224:225], 0, s[0:1]
	s_add_u32 s12, s12, 0x80080
	global_load_lds_dwordx4 v[224:225], off
	v_lshl_add_u64 v[224:225], v[226:227], 0, s[0:1]
	s_mov_b32 m0, s65
	s_addc_u32 s13, s13, 0
	global_load_lds_dwordx4 v[224:225], off
	v_lshl_add_u64 v[224:225], s[12:13], 0, v[208:209]
	s_mov_b32 m0, s68
	s_and_b64 vcc, exec, s[50:51]
	global_load_lds_dwordx4 v[224:225], off
	v_lshl_add_u64 v[224:225], s[12:13], 0, v[212:213]
	s_mov_b32 m0, s69
	s_nop 0
	global_load_lds_dwordx4 v[224:225], off
	v_lshl_add_u64 v[224:225], v[228:229], 0, s[0:1]
	s_mov_b32 m0, s66
	s_nop 0
	global_load_lds_dwordx4 v[224:225], off
	v_lshl_add_u64 v[224:225], v[230:231], 0, s[0:1]
	s_mov_b32 m0, s67
	s_nop 0
	global_load_lds_dwordx4 v[224:225], off
	s_waitcnt vmcnt(8)
	s_waitcnt lgkmcnt(0)
	s_barrier
	s_cbranch_vccnz .LBB0_259
	s_waitcnt lgkmcnt(0)
	v_mfma_f32_16x16x32_bf16 v[68:71], v[184:187], v[148:151], v[68:71]
	v_mfma_f32_16x16x32_bf16 v[68:71], v[188:191], v[164:167], v[68:71]
	v_mfma_f32_16x16x32_bf16 v[64:67], v[192:195], v[148:151], v[64:67]
	v_mfma_f32_16x16x32_bf16 v[64:67], v[196:199], v[164:167], v[64:67]
	v_mfma_f32_16x16x32_bf16 v[60:63], v[168:171], v[148:151], v[60:63]
	v_mfma_f32_16x16x32_bf16 v[60:63], v[172:175], v[164:167], v[60:63]
	v_mfma_f32_16x16x32_bf16 v[56:59], v[176:179], v[148:151], v[56:59]
	v_mfma_f32_16x16x32_bf16 v[56:59], v[180:183], v[164:167], v[56:59]
	v_mfma_f32_16x16x32_bf16 v[40:43], v[176:179], v[144:147], v[40:43]
	v_mfma_f32_16x16x32_bf16 v[40:43], v[180:183], v[160:163], v[40:43]
	v_mfma_f32_16x16x32_bf16 v[44:47], v[168:171], v[144:147], v[44:47]
	v_mfma_f32_16x16x32_bf16 v[44:47], v[172:175], v[160:163], v[44:47]
	v_mfma_f32_16x16x32_bf16 v[48:51], v[192:195], v[144:147], v[48:51]
	v_mfma_f32_16x16x32_bf16 v[48:51], v[196:199], v[160:163], v[48:51]
	v_mfma_f32_16x16x32_bf16 v[52:55], v[184:187], v[144:147], v[52:55]
	v_mfma_f32_16x16x32_bf16 v[52:55], v[188:191], v[160:163], v[52:55]
	v_mfma_f32_16x16x32_bf16 v[36:39], v[184:187], v[140:143], v[36:39]
	v_mfma_f32_16x16x32_bf16 v[36:39], v[188:191], v[156:159], v[36:39]
	v_mfma_f32_16x16x32_bf16 v[32:35], v[192:195], v[140:143], v[32:35]
	v_mfma_f32_16x16x32_bf16 v[32:35], v[196:199], v[156:159], v[32:35]
	v_mfma_f32_16x16x32_bf16 v[28:31], v[168:171], v[140:143], v[28:31]
	v_mfma_f32_16x16x32_bf16 v[28:31], v[172:175], v[156:159], v[28:31]
	v_mfma_f32_16x16x32_bf16 v[24:27], v[176:179], v[140:143], v[24:27]
	v_mfma_f32_16x16x32_bf16 v[24:27], v[180:183], v[156:159], v[24:27]
	v_mfma_f32_16x16x32_bf16 v[8:11], v[176:179], v[136:139], v[8:11]
	v_mfma_f32_16x16x32_bf16 v[8:11], v[180:183], v[152:155], v[8:11]
	v_mfma_f32_16x16x32_bf16 v[12:15], v[168:171], v[136:139], v[12:15]
	v_mfma_f32_16x16x32_bf16 v[12:15], v[172:175], v[152:155], v[12:15]
	v_mfma_f32_16x16x32_bf16 v[16:19], v[192:195], v[136:139], v[16:19]
	v_mfma_f32_16x16x32_bf16 v[16:19], v[196:199], v[152:155], v[16:19]
	v_mfma_f32_16x16x32_bf16 v[20:23], v[184:187], v[136:139], v[20:23]
	v_mfma_f32_16x16x32_bf16 v[20:23], v[188:191], v[152:155], v[20:23]
	s_branch .LBB0_259
.LBB0_259:
	s_barrier
	s_add_i32 s74, s74, 2
	s_add_u32 s62, s62, 0x100
	s_addc_u32 s63, s63, 0
	s_cmp_gt_u32 s74, 29
	s_cbranch_scc1 .LBB0_268

.LBB0_367:
	s_mov_b32 s42, s7
	s_ashr_i32 s43, s7, 31
	s_xor_b64 s[58:59], s[26:27], -1
	s_lshl_b64 s[12:13], s[42:43], 20
	s_add_u32 s7, s18, s12
	s_addc_u32 s12, s19, s13
	s_cmp_gt_i32 s37, 0
	s_cselect_b32 s13, 0x80000, 0
	s_add_u32 s48, s7, s13
	s_addc_u32 s49, s12, 0
	s_mov_b32 s36, s33
	s_and_b64 s[12:13], s[44:45], exec
	s_mov_b32 s71, s37
	s_cselect_b32 s7, s49, s25
	s_cselect_b32 s33, s48, s24
	s_ashr_i32 s37, s36, 31
	s_lshl_b64 s[12:13], s[36:37], 20
	s_add_u32 s54, s22, s12
	s_addc_u32 s55, s23, s13
	s_and_b64 s[12:13], s[44:45], exec
	s_cselect_b32 s37, s55, s51
	s_cselect_b32 s43, s54, s50
	s_cmp_gt_i32 s71, -1
	s_cselect_b64 s[56:57], -1, 0
	s_add_u32 s12, s24, 0x80
	v_cndmask_b32_e64 v2, 0, 1, s[56:57]
	v_cndmask_b32_e64 v8, 0, 1, s[26:27]
	s_addc_u32 s13, s25, 0
	v_cndmask_b32_e64 v2, v8, v2, s[44:45]
	v_lshl_add_u64 v[8:9], s[12:13], 0, v[214:215]
	v_and_b32_e32 v2, 1, v2
	v_lshl_add_u64 v[220:221], v[8:9], 0, v[218:219]
	v_lshl_add_u64 v[8:9], s[12:13], 0, v[216:217]
	v_cmp_eq_u32_e32 vcc, 1, v2
	v_lshl_add_u64 v[222:223], v[8:9], 0, v[218:219]
	s_add_u32 s26, s50, 0x100
	v_cndmask_b32_e64 v2, v246, 0, vcc
	s_addc_u32 s27, s51, 0
	s_mov_b32 s72, -2
	s_mov_b64 s[60:61], 0
	v_add_u32_e32 v168, 0x10000, v232
	v_add_u32_e32 v180, 0x14000, v232
	v_lshl_add_u64 v[224:225], v[222:223], 0, s[60:61]
	s_add_i32 m0, s9, 0xc000
	s_waitcnt lgkmcnt(0)
	ds_read_b128 v[148:151], v207
	ds_read_b128 v[164:167], v207 offset:1024
	ds_read_b128 v[144:147], v207 offset:2048
	ds_read_b128 v[160:163], v207 offset:3072
	ds_read_b128 v[140:143], v207 offset:4096
	ds_read_b128 v[156:159], v207 offset:5120
	ds_read_b128 v[136:139], v207 offset:6144
	ds_read_b128 v[152:155], v207 offset:7168
	ds_read_b128 v[184:187], v168
	ds_read_b128 v[188:191], v168 offset:1024
	ds_read_b128 v[192:195], v168 offset:2048
	ds_read_b128 v[196:199], v168 offset:3072
	ds_read_b128 v[168:171], v180
	ds_read_b128 v[172:175], v180 offset:1024
	ds_read_b128 v[176:179], v180 offset:2048
	ds_read_b128 v[180:183], v180 offset:3072
	global_load_lds_dwordx4 v[224:225], off
	v_lshl_add_u64 v[224:225], v[220:221], 0, s[60:61]
	s_add_i32 m0, s9, 0xe000
	s_nop 0
	global_load_lds_dwordx4 v[224:225], off
	s_waitcnt vmcnt(8)
	s_waitcnt lgkmcnt(0)
	s_barrier
	s_waitcnt lgkmcnt(0)
	v_mfma_f32_16x16x32_bf16 v[132:135], v[184:187], v[148:151], 0
	v_mfma_f32_16x16x32_bf16 v[132:135], v[188:191], v[164:167], v[132:135]
	v_mfma_f32_16x16x32_bf16 v[128:131], v[192:195], v[148:151], 0
	v_mfma_f32_16x16x32_bf16 v[128:131], v[196:199], v[164:167], v[128:131]
	v_mfma_f32_16x16x32_bf16 v[116:119], v[168:171], v[148:151], 0
	v_mfma_f32_16x16x32_bf16 v[116:119], v[172:175], v[164:167], v[116:119]
	v_mfma_f32_16x16x32_bf16 v[112:115], v[176:179], v[148:151], 0
	v_mfma_f32_16x16x32_bf16 v[112:115], v[180:183], v[164:167], v[112:115]
	v_mfma_f32_16x16x32_bf16 v[96:99], v[176:179], v[144:147], 0
	v_mfma_f32_16x16x32_bf16 v[96:99], v[180:183], v[160:163], v[96:99]
	v_mfma_f32_16x16x32_bf16 v[100:103], v[168:171], v[144:147], 0
	v_mfma_f32_16x16x32_bf16 v[100:103], v[172:175], v[160:163], v[100:103]
	v_mfma_f32_16x16x32_bf16 v[120:123], v[192:195], v[144:147], 0
	v_mfma_f32_16x16x32_bf16 v[120:123], v[196:199], v[160:163], v[120:123]
	v_mfma_f32_16x16x32_bf16 v[124:127], v[184:187], v[144:147], 0
	v_mfma_f32_16x16x32_bf16 v[124:127], v[188:191], v[160:163], v[124:127]
	v_mfma_f32_16x16x32_bf16 v[108:111], v[184:187], v[140:143], 0
	v_mfma_f32_16x16x32_bf16 v[108:111], v[188:191], v[156:159], v[108:111]
	v_mfma_f32_16x16x32_bf16 v[104:107], v[192:195], v[140:143], 0
	v_mfma_f32_16x16x32_bf16 v[104:107], v[196:199], v[156:159], v[104:107]
	v_mfma_f32_16x16x32_bf16 v[84:87], v[168:171], v[140:143], 0
	v_mfma_f32_16x16x32_bf16 v[84:87], v[172:175], v[156:159], v[84:87]
	v_mfma_f32_16x16x32_bf16 v[80:83], v[176:179], v[140:143], 0
	v_mfma_f32_16x16x32_bf16 v[80:83], v[180:183], v[156:159], v[80:83]
	v_mfma_f32_16x16x32_bf16 v[72:75], v[176:179], v[136:139], 0
	v_mfma_f32_16x16x32_bf16 v[72:75], v[180:183], v[152:155], v[72:75]
	v_mfma_f32_16x16x32_bf16 v[76:79], v[168:171], v[136:139], 0
	v_mfma_f32_16x16x32_bf16 v[76:79], v[172:175], v[152:155], v[76:79]
	v_mfma_f32_16x16x32_bf16 v[88:91], v[192:195], v[136:139], 0
	v_mfma_f32_16x16x32_bf16 v[88:91], v[196:199], v[152:155], v[88:91]
	v_mfma_f32_16x16x32_bf16 v[92:95], v[184:187], v[136:139], 0
	v_mfma_f32_16x16x32_bf16 v[92:95], v[188:191], v[152:155], v[92:95]
	s_barrier
	v_cndmask_b32_e64 v204, 0, 1, s[58:59]
	v_cmp_ne_u32_e64 s[50:51], 1, v204
	s_andn2_b64 vcc, exec, s[58:59]
	s_cbranch_vccnz .Lpeel1_371
	ds_read_b128 v[148:151], v207 offset:16384
	ds_read_b128 v[164:167], v207 offset:17408
	ds_read_b128 v[144:147], v207 offset:18432
	ds_read_b128 v[160:163], v207 offset:19456
	ds_read_b128 v[140:143], v207 offset:20480
	ds_read_b128 v[156:159], v207 offset:21504
	ds_read_b128 v[136:139], v207 offset:22528
	ds_read_b128 v[152:155], v207 offset:23552
.Lpeel1_371:
	s_add_u32 s12, s24, s60
	s_addc_u32 s13, s25, s61
	s_add_u32 s14, s12, 0x100
	s_addc_u32 s15, s13, 0
	s_add_u32 s73, s26, s60
	s_addc_u32 s74, s27, s61
	s_cmpk_eq_i32 s60, 0xf00
	s_cselect_b64 s[52:53], -1, 0
	s_and_b64 s[12:13], s[52:53], exec
	s_cselect_b32 s13, s37, s74
	s_cselect_b32 s12, s43, s73
	s_mov_b32 m0, s38
	s_cselect_b32 s15, s7, s15
	s_cselect_b32 s14, s33, s14
	v_lshl_add_u64 v[224:225], s[12:13], 0, v[208:209]
	s_add_u32 s74, s12, 0x80000
	global_load_lds_dwordx4 v[224:225], off
	v_lshl_add_u64 v[226:227], s[12:13], 0, v[212:213]
	s_mov_b32 m0, s39
	s_addc_u32 s75, s13, 0
	global_load_lds_dwordx4 v[226:227], off
	v_lshl_add_u64 v[228:229], s[74:75], 0, v[208:209]
	s_mov_b32 m0, s40
	v_lshl_add_u64 v[230:231], s[14:15], 0, v[210:211]
	global_load_lds_dwordx4 v[228:229], off
	v_lshl_add_u64 v[228:229], s[74:75], 0, v[212:213]
	s_mov_b32 m0, s41
	s_and_b64 vcc, exec, s[50:51]
	global_load_lds_dwordx4 v[228:229], off
	v_lshl_add_u64 v[228:229], s[14:15], 0, v[4:5]
	s_mov_b32 m0, s9
	s_nop 0
	global_load_lds_dwordx4 v[228:229], off
	s_mov_b32 m0, s47
	s_nop 0
	global_load_lds_dwordx4 v[230:231], off
	s_waitcnt vmcnt(8)
	s_waitcnt lgkmcnt(0)
	s_barrier
	s_cbranch_vccnz .Lpeel1_373
	s_waitcnt lgkmcnt(0)
	v_mfma_f32_16x16x32_bf16 v[68:71], v[184:187], v[148:151], 0
	v_mfma_f32_16x16x32_bf16 v[68:71], v[188:191], v[164:167], v[68:71]
	v_mfma_f32_16x16x32_bf16 v[64:67], v[192:195], v[148:151], 0
	v_mfma_f32_16x16x32_bf16 v[64:67], v[196:199], v[164:167], v[64:67]
	v_mfma_f32_16x16x32_bf16 v[60:63], v[168:171], v[148:151], 0
	v_mfma_f32_16x16x32_bf16 v[60:63], v[172:175], v[164:167], v[60:63]
	v_mfma_f32_16x16x32_bf16 v[56:59], v[176:179], v[148:151], 0
	v_mfma_f32_16x16x32_bf16 v[56:59], v[180:183], v[164:167], v[56:59]
	v_mfma_f32_16x16x32_bf16 v[40:43], v[176:179], v[144:147], 0
	v_mfma_f32_16x16x32_bf16 v[40:43], v[180:183], v[160:163], v[40:43]
	v_mfma_f32_16x16x32_bf16 v[44:47], v[168:171], v[144:147], 0
	v_mfma_f32_16x16x32_bf16 v[44:47], v[172:175], v[160:163], v[44:47]
	v_mfma_f32_16x16x32_bf16 v[48:51], v[192:195], v[144:147], 0
	v_mfma_f32_16x16x32_bf16 v[48:51], v[196:199], v[160:163], v[48:51]
	v_mfma_f32_16x16x32_bf16 v[52:55], v[184:187], v[144:147], 0
	v_mfma_f32_16x16x32_bf16 v[52:55], v[188:191], v[160:163], v[52:55]
	v_mfma_f32_16x16x32_bf16 v[36:39], v[184:187], v[140:143], 0
	v_mfma_f32_16x16x32_bf16 v[36:39], v[188:191], v[156:159], v[36:39]
	v_mfma_f32_16x16x32_bf16 v[32:35], v[192:195], v[140:143], 0
	v_mfma_f32_16x16x32_bf16 v[32:35], v[196:199], v[156:159], v[32:35]
	v_mfma_f32_16x16x32_bf16 v[28:31], v[168:171], v[140:143], 0
	v_mfma_f32_16x16x32_bf16 v[28:31], v[172:175], v[156:159], v[28:31]
	v_mfma_f32_16x16x32_bf16 v[24:27], v[176:179], v[140:143], 0
	v_mfma_f32_16x16x32_bf16 v[24:27], v[180:183], v[156:159], v[24:27]
	v_mfma_f32_16x16x32_bf16 v[8:11], v[176:179], v[136:139], 0
	v_mfma_f32_16x16x32_bf16 v[8:11], v[180:183], v[152:155], v[8:11]
	v_mfma_f32_16x16x32_bf16 v[12:15], v[168:171], v[136:139], 0
	v_mfma_f32_16x16x32_bf16 v[12:15], v[172:175], v[152:155], v[12:15]
	v_mfma_f32_16x16x32_bf16 v[16:19], v[192:195], v[136:139], 0
	v_mfma_f32_16x16x32_bf16 v[16:19], v[196:199], v[152:155], v[16:19]
	v_mfma_f32_16x16x32_bf16 v[20:23], v[184:187], v[136:139], 0
	v_mfma_f32_16x16x32_bf16 v[20:23], v[188:191], v[152:155], v[20:23]

.Lpeel1_375:
	s_mov_b32 m0, s64
	v_lshl_add_u64 v[224:225], v[224:225], 0, s[0:1]
	s_add_u32 s12, s12, 0x80080
	global_load_lds_dwordx4 v[224:225], off
	v_lshl_add_u64 v[224:225], v[226:227], 0, s[0:1]
	s_mov_b32 m0, s65
	s_addc_u32 s13, s13, 0
	global_load_lds_dwordx4 v[224:225], off
	v_lshl_add_u64 v[224:225], s[12:13], 0, v[208:209]
	s_mov_b32 m0, s68
	s_and_b64 vcc, exec, s[50:51]
	global_load_lds_dwordx4 v[224:225], off
	v_lshl_add_u64 v[224:225], s[12:13], 0, v[212:213]
	s_mov_b32 m0, s69
	s_nop 0
	global_load_lds_dwordx4 v[224:225], off
	v_lshl_add_u64 v[224:225], v[228:229], 0, s[0:1]
	s_mov_b32 m0, s66
	s_nop 0
	global_load_lds_dwordx4 v[224:225], off
	v_lshl_add_u64 v[224:225], v[230:231], 0, s[0:1]
	s_mov_b32 m0, s67
	s_nop 0
	global_load_lds_dwordx4 v[224:225], off
	s_waitcnt vmcnt(8)
	s_waitcnt lgkmcnt(0)
	s_barrier
	s_cbranch_vccnz .LBB0_368
	s_waitcnt lgkmcnt(0)
	v_mfma_f32_16x16x32_bf16 v[68:71], v[184:187], v[148:151], v[68:71]
	v_mfma_f32_16x16x32_bf16 v[68:71], v[188:191], v[164:167], v[68:71]
	v_mfma_f32_16x16x32_bf16 v[64:67], v[192:195], v[148:151], v[64:67]
	v_mfma_f32_16x16x32_bf16 v[64:67], v[196:199], v[164:167], v[64:67]
	v_mfma_f32_16x16x32_bf16 v[60:63], v[168:171], v[148:151], v[60:63]
	v_mfma_f32_16x16x32_bf16 v[60:63], v[172:175], v[164:167], v[60:63]
	v_mfma_f32_16x16x32_bf16 v[56:59], v[176:179], v[148:151], v[56:59]
	v_mfma_f32_16x16x32_bf16 v[56:59], v[180:183], v[164:167], v[56:59]
	v_mfma_f32_16x16x32_bf16 v[40:43], v[176:179], v[144:147], v[40:43]
	v_mfma_f32_16x16x32_bf16 v[40:43], v[180:183], v[160:163], v[40:43]
	v_mfma_f32_16x16x32_bf16 v[44:47], v[168:171], v[144:147], v[44:47]
	v_mfma_f32_16x16x32_bf16 v[44:47], v[172:175], v[160:163], v[44:47]
	v_mfma_f32_16x16x32_bf16 v[48:51], v[192:195], v[144:147], v[48:51]
	v_mfma_f32_16x16x32_bf16 v[48:51], v[196:199], v[160:163], v[48:51]
	v_mfma_f32_16x16x32_bf16 v[52:55], v[184:187], v[144:147], v[52:55]
	v_mfma_f32_16x16x32_bf16 v[52:55], v[188:191], v[160:163], v[52:55]
	v_mfma_f32_16x16x32_bf16 v[36:39], v[184:187], v[140:143], v[36:39]
	v_mfma_f32_16x16x32_bf16 v[36:39], v[188:191], v[156:159], v[36:39]
	v_mfma_f32_16x16x32_bf16 v[32:35], v[192:195], v[140:143], v[32:35]
	v_mfma_f32_16x16x32_bf16 v[32:35], v[196:199], v[156:159], v[32:35]
	v_mfma_f32_16x16x32_bf16 v[28:31], v[168:171], v[140:143], v[28:31]
	v_mfma_f32_16x16x32_bf16 v[28:31], v[172:175], v[156:159], v[28:31]
	v_mfma_f32_16x16x32_bf16 v[24:27], v[176:179], v[140:143], v[24:27]
	v_mfma_f32_16x16x32_bf16 v[24:27], v[180:183], v[156:159], v[24:27]
	v_mfma_f32_16x16x32_bf16 v[8:11], v[176:179], v[136:139], v[8:11]
	v_mfma_f32_16x16x32_bf16 v[8:11], v[180:183], v[152:155], v[8:11]
	v_mfma_f32_16x16x32_bf16 v[12:15], v[168:171], v[136:139], v[12:15]
	v_mfma_f32_16x16x32_bf16 v[12:15], v[172:175], v[152:155], v[12:15]
	v_mfma_f32_16x16x32_bf16 v[16:19], v[192:195], v[136:139], v[16:19]
	v_mfma_f32_16x16x32_bf16 v[16:19], v[196:199], v[152:155], v[16:19]
	v_mfma_f32_16x16x32_bf16 v[20:23], v[184:187], v[136:139], v[20:23]
	v_mfma_f32_16x16x32_bf16 v[20:23], v[188:191], v[152:155], v[20:23]
	s_branch .LBB0_368
.LBB0_368:
	s_barrier
	s_add_i32 s72, s72, 2
	s_add_u32 s60, s60, 0x100
	s_addc_u32 s61, s61, 0
	s_cmp_gt_u32 s72, 29
	s_cbranch_scc1 .LBB0_377

.LBB0_557:
	s_mov_b32 s20, s17
	s_mov_b32 s16, s21
	s_ashr_i32 s21, s17, 31
	s_xor_b64 s[62:63], s[26:27], -1
	s_lshl_b64 s[12:13], s[20:21], 18
	s_add_u32 s12, s18, s12
	s_addc_u32 s13, s19, s13
	s_cmp_gt_i32 s33, 0
	s_cselect_b32 s14, 0x20000, 0
	s_add_u32 s42, s12, s14
	s_addc_u32 s43, s13, 0
	s_and_b64 s[12:13], s[24:25], exec
	s_mov_b32 s77, s33
	s_cselect_b32 s21, s43, s61
	s_cselect_b32 s33, s42, s60
	s_ashr_i32 s17, s16, 31
	s_lshl_b64 s[12:13], s[16:17], 18
	s_add_u32 s44, s22, s12
	s_addc_u32 s45, s23, s13
	s_and_b64 s[12:13], s[24:25], exec
	s_cselect_b32 s17, s45, s51
	s_cselect_b32 s35, s44, s50
	s_cmp_gt_i32 s77, -1
	s_cselect_b64 s[48:49], -1, 0
	s_add_u32 s12, s60, 0x80
	v_cndmask_b32_e64 v2, 0, 1, s[48:49]
	v_cndmask_b32_e64 v8, 0, 1, s[26:27]
	s_addc_u32 s13, s61, 0
	v_cndmask_b32_e64 v2, v8, v2, s[24:25]
	v_lshl_add_u64 v[8:9], s[12:13], 0, v[216:217]
	v_and_b32_e32 v2, 1, v2
	v_lshl_add_u64 v[222:223], v[8:9], 0, v[220:221]
	v_lshl_add_u64 v[8:9], s[12:13], 0, v[218:219]
	v_cmp_eq_u32_e32 vcc, 1, v2
	v_mov_b32_e32 v2, 0x20000
	v_lshl_add_u64 v[224:225], v[8:9], 0, v[220:221]
	s_add_u32 s26, s50, 0x100
	v_cndmask_b32_e64 v2, v2, 0, vcc
	s_addc_u32 s27, s51, 0
	s_mov_b32 s57, -2
	s_mov_b64 s[64:65], 0
	v_add_u32_e32 v168, 0x10000, v240
	v_add_u32_e32 v180, 0x14000, v240
	v_lshl_add_u64 v[226:227], v[224:225], 0, s[64:65]
	s_add_i32 m0, s38, 0xc000
	s_waitcnt lgkmcnt(0)
	ds_read_b128 v[148:151], v239
	ds_read_b128 v[164:167], v239 offset:1024
	ds_read_b128 v[144:147], v239 offset:2048
	ds_read_b128 v[160:163], v239 offset:3072
	ds_read_b128 v[140:143], v239 offset:4096
	ds_read_b128 v[156:159], v239 offset:5120
	ds_read_b128 v[136:139], v239 offset:6144
	ds_read_b128 v[152:155], v239 offset:7168
	ds_read_b128 v[184:187], v168
	ds_read_b128 v[188:191], v168 offset:1024
	ds_read_b128 v[192:195], v168 offset:2048
	ds_read_b128 v[196:199], v168 offset:3072
	ds_read_b128 v[168:171], v180
	ds_read_b128 v[172:175], v180 offset:1024
	ds_read_b128 v[176:179], v180 offset:2048
	ds_read_b128 v[180:183], v180 offset:3072
	global_load_lds_dwordx4 v[226:227], off
	v_lshl_add_u64 v[226:227], v[222:223], 0, s[64:65]
	s_add_i32 m0, s38, 0xe000
	s_nop 0
	global_load_lds_dwordx4 v[226:227], off
	s_waitcnt vmcnt(8)
	s_waitcnt lgkmcnt(0)
	s_barrier
	s_waitcnt lgkmcnt(0)
	v_mfma_f32_16x16x32_bf16 v[132:135], v[184:187], v[148:151], 0
	v_mfma_f32_16x16x32_bf16 v[132:135], v[188:191], v[164:167], v[132:135]
	v_mfma_f32_16x16x32_bf16 v[128:131], v[192:195], v[148:151], 0
	v_mfma_f32_16x16x32_bf16 v[128:131], v[196:199], v[164:167], v[128:131]
	v_mfma_f32_16x16x32_bf16 v[124:127], v[168:171], v[148:151], 0
	v_mfma_f32_16x16x32_bf16 v[124:127], v[172:175], v[164:167], v[124:127]
	v_mfma_f32_16x16x32_bf16 v[120:123], v[176:179], v[148:151], 0
	v_mfma_f32_16x16x32_bf16 v[120:123], v[180:183], v[164:167], v[120:123]
	v_mfma_f32_16x16x32_bf16 v[104:107], v[176:179], v[144:147], 0
	v_mfma_f32_16x16x32_bf16 v[104:107], v[180:183], v[160:163], v[104:107]
	v_mfma_f32_16x16x32_bf16 v[108:111], v[168:171], v[144:147], 0
	v_mfma_f32_16x16x32_bf16 v[108:111], v[172:175], v[160:163], v[108:111]
	v_mfma_f32_16x16x32_bf16 v[112:115], v[192:195], v[144:147], 0
	v_mfma_f32_16x16x32_bf16 v[112:115], v[196:199], v[160:163], v[112:115]
	v_mfma_f32_16x16x32_bf16 v[116:119], v[184:187], v[144:147], 0
	v_mfma_f32_16x16x32_bf16 v[116:119], v[188:191], v[160:163], v[116:119]
	v_mfma_f32_16x16x32_bf16 v[100:103], v[184:187], v[140:143], 0
	v_mfma_f32_16x16x32_bf16 v[100:103], v[188:191], v[156:159], v[100:103]
	v_mfma_f32_16x16x32_bf16 v[96:99], v[192:195], v[140:143], 0
	v_mfma_f32_16x16x32_bf16 v[96:99], v[196:199], v[156:159], v[96:99]
	v_mfma_f32_16x16x32_bf16 v[92:95], v[168:171], v[140:143], 0
	v_mfma_f32_16x16x32_bf16 v[92:95], v[172:175], v[156:159], v[92:95]
	v_mfma_f32_16x16x32_bf16 v[88:91], v[176:179], v[140:143], 0
	v_mfma_f32_16x16x32_bf16 v[88:91], v[180:183], v[156:159], v[88:91]
	v_mfma_f32_16x16x32_bf16 v[72:75], v[176:179], v[136:139], 0
	v_mfma_f32_16x16x32_bf16 v[72:75], v[180:183], v[152:155], v[72:75]
	v_mfma_f32_16x16x32_bf16 v[76:79], v[168:171], v[136:139], 0
	v_mfma_f32_16x16x32_bf16 v[76:79], v[172:175], v[152:155], v[76:79]
	v_mfma_f32_16x16x32_bf16 v[80:83], v[192:195], v[136:139], 0
	v_mfma_f32_16x16x32_bf16 v[80:83], v[196:199], v[152:155], v[80:83]
	v_mfma_f32_16x16x32_bf16 v[84:87], v[184:187], v[136:139], 0
	v_mfma_f32_16x16x32_bf16 v[84:87], v[188:191], v[152:155], v[84:87]
	s_barrier
	v_cndmask_b32_e64 v204, 0, 1, s[62:63]
	v_cmp_ne_u32_e64 s[50:51], 1, v204
	s_andn2_b64 vcc, exec, s[62:63]
	s_cbranch_vccnz .Lpeel2_561
	ds_read_b128 v[148:151], v239 offset:16384
	ds_read_b128 v[164:167], v239 offset:17408
	ds_read_b128 v[144:147], v239 offset:18432
	ds_read_b128 v[160:163], v239 offset:19456
	ds_read_b128 v[140:143], v239 offset:20480
	ds_read_b128 v[156:159], v239 offset:21504
	ds_read_b128 v[136:139], v239 offset:22528
	ds_read_b128 v[152:155], v239 offset:23552
.Lpeel2_561:
	s_add_u32 s12, s60, s64
	s_addc_u32 s13, s61, s65
	s_add_u32 s14, s12, 0x100
	s_addc_u32 s15, s13, 0
	s_add_u32 s79, s26, s64
	s_addc_u32 s80, s27, s65
	s_cmpk_eq_i32 s64, 0x300
	s_cselect_b64 s[52:53], -1, 0
	s_and_b64 s[12:13], s[52:53], exec
	s_cselect_b32 s13, s17, s80
	s_cselect_b32 s12, s35, s79
	s_mov_b32 m0, s39
	s_cselect_b32 s15, s21, s15
	s_cselect_b32 s14, s33, s14
	v_lshl_add_u64 v[226:227], s[12:13], 0, v[4:5]
	s_add_u32 s80, s12, 0x20000
	global_load_lds_dwordx4 v[226:227], off
	v_lshl_add_u64 v[228:229], s[12:13], 0, v[208:209]
	s_mov_b32 m0, s40
	s_addc_u32 s81, s13, 0
	global_load_lds_dwordx4 v[228:229], off
	v_lshl_add_u64 v[230:231], s[80:81], 0, v[4:5]
	s_mov_b32 m0, s41
	v_lshl_add_u64 v[232:233], s[14:15], 0, v[208:209]
	global_load_lds_dwordx4 v[230:231], off
	v_lshl_add_u64 v[230:231], s[80:81], 0, v[208:209]
	s_mov_b32 m0, s47
	s_and_b64 vcc, exec, s[50:51]
	global_load_lds_dwordx4 v[230:231], off
	v_lshl_add_u64 v[230:231], s[14:15], 0, v[4:5]
	s_mov_b32 m0, s38
	s_nop 0
	global_load_lds_dwordx4 v[230:231], off
	s_mov_b32 m0, s59
	s_nop 0
	global_load_lds_dwordx4 v[232:233], off
	s_waitcnt vmcnt(8)
	s_waitcnt lgkmcnt(0)
	s_barrier
	s_cbranch_vccnz .Lpeel2_563
	s_waitcnt lgkmcnt(0)
	v_mfma_f32_16x16x32_bf16 v[68:71], v[184:187], v[148:151], 0
	v_mfma_f32_16x16x32_bf16 v[68:71], v[188:191], v[164:167], v[68:71]
	v_mfma_f32_16x16x32_bf16 v[64:67], v[192:195], v[148:151], 0
	v_mfma_f32_16x16x32_bf16 v[64:67], v[196:199], v[164:167], v[64:67]
	v_mfma_f32_16x16x32_bf16 v[60:63], v[168:171], v[148:151], 0
	v_mfma_f32_16x16x32_bf16 v[60:63], v[172:175], v[164:167], v[60:63]
	v_mfma_f32_16x16x32_bf16 v[56:59], v[176:179], v[148:151], 0
	v_mfma_f32_16x16x32_bf16 v[56:59], v[180:183], v[164:167], v[56:59]
	v_mfma_f32_16x16x32_bf16 v[40:43], v[176:179], v[144:147], 0
	v_mfma_f32_16x16x32_bf16 v[40:43], v[180:183], v[160:163], v[40:43]
	v_mfma_f32_16x16x32_bf16 v[44:47], v[168:171], v[144:147], 0
	v_mfma_f32_16x16x32_bf16 v[44:47], v[172:175], v[160:163], v[44:47]
	v_mfma_f32_16x16x32_bf16 v[48:51], v[192:195], v[144:147], 0
	v_mfma_f32_16x16x32_bf16 v[48:51], v[196:199], v[160:163], v[48:51]
	v_mfma_f32_16x16x32_bf16 v[52:55], v[184:187], v[144:147], 0
	v_mfma_f32_16x16x32_bf16 v[52:55], v[188:191], v[160:163], v[52:55]
	v_mfma_f32_16x16x32_bf16 v[36:39], v[184:187], v[140:143], 0
	v_mfma_f32_16x16x32_bf16 v[36:39], v[188:191], v[156:159], v[36:39]
	v_mfma_f32_16x16x32_bf16 v[32:35], v[192:195], v[140:143], 0
	v_mfma_f32_16x16x32_bf16 v[32:35], v[196:199], v[156:159], v[32:35]
	v_mfma_f32_16x16x32_bf16 v[28:31], v[168:171], v[140:143], 0
	v_mfma_f32_16x16x32_bf16 v[28:31], v[172:175], v[156:159], v[28:31]
	v_mfma_f32_16x16x32_bf16 v[24:27], v[176:179], v[140:143], 0
	v_mfma_f32_16x16x32_bf16 v[24:27], v[180:183], v[156:159], v[24:27]
	v_mfma_f32_16x16x32_bf16 v[8:11], v[176:179], v[136:139], 0
	v_mfma_f32_16x16x32_bf16 v[8:11], v[180:183], v[152:155], v[8:11]
	v_mfma_f32_16x16x32_bf16 v[12:15], v[168:171], v[136:139], 0
	v_mfma_f32_16x16x32_bf16 v[12:15], v[172:175], v[152:155], v[12:15]
	v_mfma_f32_16x16x32_bf16 v[16:19], v[192:195], v[136:139], 0
	v_mfma_f32_16x16x32_bf16 v[16:19], v[196:199], v[152:155], v[16:19]
	v_mfma_f32_16x16x32_bf16 v[20:23], v[184:187], v[136:139], 0
	v_mfma_f32_16x16x32_bf16 v[20:23], v[188:191], v[152:155], v[20:23]

.Lpeel2_565:
	s_mov_b32 m0, s70
	v_lshl_add_u64 v[204:205], v[226:227], 0, s[0:1]
	s_add_u32 s12, s12, 0x20080
	global_load_lds_dwordx4 v[204:205], off
	v_lshl_add_u64 v[204:205], v[228:229], 0, s[0:1]
	s_mov_b32 m0, s71
	s_addc_u32 s13, s13, 0
	global_load_lds_dwordx4 v[204:205], off
	v_lshl_add_u64 v[204:205], s[12:13], 0, v[4:5]
	s_mov_b32 m0, s74
	s_and_b64 vcc, exec, s[50:51]
	global_load_lds_dwordx4 v[204:205], off
	v_lshl_add_u64 v[204:205], s[12:13], 0, v[208:209]
	s_mov_b32 m0, s75
	s_nop 0
	global_load_lds_dwordx4 v[204:205], off
	v_lshl_add_u64 v[204:205], v[230:231], 0, s[0:1]
	s_mov_b32 m0, s72
	s_nop 0
	global_load_lds_dwordx4 v[204:205], off
	v_lshl_add_u64 v[204:205], v[232:233], 0, s[0:1]
	s_mov_b32 m0, s73
	s_nop 0
	global_load_lds_dwordx4 v[204:205], off
	s_waitcnt vmcnt(8)
	s_waitcnt lgkmcnt(0)
	s_barrier
	s_cbranch_vccnz .LBB0_558
	s_waitcnt lgkmcnt(0)
	v_mfma_f32_16x16x32_bf16 v[68:71], v[184:187], v[148:151], v[68:71]
	v_mfma_f32_16x16x32_bf16 v[68:71], v[188:191], v[164:167], v[68:71]
	v_mfma_f32_16x16x32_bf16 v[64:67], v[192:195], v[148:151], v[64:67]
	v_mfma_f32_16x16x32_bf16 v[64:67], v[196:199], v[164:167], v[64:67]
	v_mfma_f32_16x16x32_bf16 v[60:63], v[168:171], v[148:151], v[60:63]
	v_mfma_f32_16x16x32_bf16 v[60:63], v[172:175], v[164:167], v[60:63]
	v_mfma_f32_16x16x32_bf16 v[56:59], v[176:179], v[148:151], v[56:59]
	v_mfma_f32_16x16x32_bf16 v[56:59], v[180:183], v[164:167], v[56:59]
	v_mfma_f32_16x16x32_bf16 v[40:43], v[176:179], v[144:147], v[40:43]
	v_mfma_f32_16x16x32_bf16 v[40:43], v[180:183], v[160:163], v[40:43]
	v_mfma_f32_16x16x32_bf16 v[44:47], v[168:171], v[144:147], v[44:47]
	v_mfma_f32_16x16x32_bf16 v[44:47], v[172:175], v[160:163], v[44:47]
	v_mfma_f32_16x16x32_bf16 v[48:51], v[192:195], v[144:147], v[48:51]
	v_mfma_f32_16x16x32_bf16 v[48:51], v[196:199], v[160:163], v[48:51]
	v_mfma_f32_16x16x32_bf16 v[52:55], v[184:187], v[144:147], v[52:55]
	v_mfma_f32_16x16x32_bf16 v[52:55], v[188:191], v[160:163], v[52:55]
	v_mfma_f32_16x16x32_bf16 v[36:39], v[184:187], v[140:143], v[36:39]
	v_mfma_f32_16x16x32_bf16 v[36:39], v[188:191], v[156:159], v[36:39]
	v_mfma_f32_16x16x32_bf16 v[32:35], v[192:195], v[140:143], v[32:35]
	v_mfma_f32_16x16x32_bf16 v[32:35], v[196:199], v[156:159], v[32:35]
	v_mfma_f32_16x16x32_bf16 v[28:31], v[168:171], v[140:143], v[28:31]
	v_mfma_f32_16x16x32_bf16 v[28:31], v[172:175], v[156:159], v[28:31]
	v_mfma_f32_16x16x32_bf16 v[24:27], v[176:179], v[140:143], v[24:27]
	v_mfma_f32_16x16x32_bf16 v[24:27], v[180:183], v[156:159], v[24:27]
	v_mfma_f32_16x16x32_bf16 v[8:11], v[176:179], v[136:139], v[8:11]
	v_mfma_f32_16x16x32_bf16 v[8:11], v[180:183], v[152:155], v[8:11]
	v_mfma_f32_16x16x32_bf16 v[12:15], v[168:171], v[136:139], v[12:15]
	v_mfma_f32_16x16x32_bf16 v[12:15], v[172:175], v[152:155], v[12:15]
	v_mfma_f32_16x16x32_bf16 v[16:19], v[192:195], v[136:139], v[16:19]
	v_mfma_f32_16x16x32_bf16 v[16:19], v[196:199], v[152:155], v[16:19]
	v_mfma_f32_16x16x32_bf16 v[20:23], v[184:187], v[136:139], v[20:23]
	v_mfma_f32_16x16x32_bf16 v[20:23], v[188:191], v[152:155], v[20:23]
	s_branch .LBB0_558
.LBB0_558:
	s_barrier
	s_add_i32 s57, s57, 2
	s_add_u32 s64, s64, 0x100
	s_addc_u32 s65, s65, 0
	s_cmp_gt_u32 s57, 5
	s_cbranch_scc1 .LBB0_567

.LBB0_619:
	s_ashr_i32 s17, s16, 31
	s_lshl_b64 s[14:15], s[16:17], 18
	s_add_u32 s20, s18, s14
	s_addc_u32 s21, s19, s15
	s_and_b64 s[14:15], s[50:51], exec
	s_cselect_b32 s17, s21, s13
	s_cselect_b32 s33, s20, s12
	s_ashr_i32 s11, s10, 31
	s_lshl_b64 s[14:15], s[10:11], 18
	s_add_u32 s24, s22, s14
	s_addc_u32 s25, s23, s15
	s_and_b64 s[14:15], s[50:51], exec
	s_cselect_b32 s11, s25, s27
	s_cselect_b32 s37, s24, s26
	s_add_u32 s42, s12, 0x20080
	s_addc_u32 s43, s13, 0
	s_add_u32 s26, s26, 0x100
	v_mov_b32_e32 v8, 0
	s_addc_u32 s27, s27, 0
	s_mov_b32 s57, -2
	s_add_u32 s12, s42, 0xfffe0080
	s_addc_u32 s13, s43, -1
	s_cmp_eq_u32 s57, 4
	s_cselect_b32 s15, s17, s13
	s_cselect_b32 s14, s33, s12
	s_cselect_b32 s13, s11, s27
	s_cselect_b32 s12, s37, s26
	s_add_i32 s58, 0, 0x10000
	v_add_u32_e32 v136, s58, v1
	s_add_i32 s60, 0, 0x14000
	ds_read_b128 v[150:153], v7
	ds_read_b128 v[154:157], v7 offset:1024
	ds_read_b128 v[158:161], v7 offset:2048
	ds_read_b128 v[162:165], v7 offset:3072
	ds_read_b128 v[166:169], v7 offset:4096
	ds_read_b128 v[170:173], v7 offset:5120
	ds_read_b128 v[174:177], v7 offset:6144
	ds_read_b128 v[178:181], v7 offset:7168
	ds_read_b128 v[182:185], v136
	ds_read_b128 v[186:189], v136 offset:1024
	ds_read_b128 v[190:193], v136 offset:2048
	ds_read_b128 v[194:197], v136 offset:3072
	v_add_u32_e32 v136, s60, v1
	ds_read_b128 v[208:211], v136
	ds_read_b128 v[212:215], v136 offset:1024
	ds_read_b128 v[216:219], v136 offset:2048
	ds_read_b128 v[220:223], v136 offset:3072
	v_lshl_add_u64 v[136:137], s[42:43], 0, v[146:147]
	s_add_i32 m0, s38, 0xc000
	s_nop 0
	global_load_lds_dwordx4 v[136:137], off
	v_lshl_add_u64 v[136:137], s[42:43], 0, v[148:149]
	s_add_i32 m0, s38, 0xe000
	s_nop 0
	global_load_lds_dwordx4 v[136:137], off
	s_waitcnt vmcnt(8)
	s_waitcnt lgkmcnt(0)
	s_barrier
	s_waitcnt lgkmcnt(0)
	v_mfma_f32_16x16x32_bf16 v[132:135], v[182:185], v[150:153], 0
	v_mfma_f32_16x16x32_bf16 v[132:135], v[186:189], v[154:157], v[132:135]
	v_mfma_f32_16x16x32_bf16 v[128:131], v[190:193], v[150:153], 0
	v_mfma_f32_16x16x32_bf16 v[128:131], v[194:197], v[154:157], v[128:131]
	v_mfma_f32_16x16x32_bf16 v[112:115], v[208:211], v[150:153], 0
	v_mfma_f32_16x16x32_bf16 v[112:115], v[212:215], v[154:157], v[112:115]
	v_mfma_f32_16x16x32_bf16 v[104:107], v[216:219], v[150:153], 0
	v_mfma_f32_16x16x32_bf16 v[104:107], v[220:223], v[154:157], v[104:107]
	v_mfma_f32_16x16x32_bf16 v[88:91], v[216:219], v[158:161], 0
	v_mfma_f32_16x16x32_bf16 v[88:91], v[220:223], v[162:165], v[88:91]
	v_mfma_f32_16x16x32_bf16 v[96:99], v[208:211], v[158:161], 0
	v_mfma_f32_16x16x32_bf16 v[96:99], v[212:215], v[162:165], v[96:99]
	v_mfma_f32_16x16x32_bf16 v[120:123], v[190:193], v[158:161], 0
	v_mfma_f32_16x16x32_bf16 v[120:123], v[194:197], v[162:165], v[120:123]
	v_mfma_f32_16x16x32_bf16 v[124:127], v[182:185], v[158:161], 0
	v_mfma_f32_16x16x32_bf16 v[124:127], v[186:189], v[162:165], v[124:127]
	v_mfma_f32_16x16x32_bf16 v[116:119], v[182:185], v[166:169], 0
	v_mfma_f32_16x16x32_bf16 v[116:119], v[186:189], v[170:173], v[116:119]
	v_mfma_f32_16x16x32_bf16 v[108:111], v[190:193], v[166:169], 0
	v_mfma_f32_16x16x32_bf16 v[108:111], v[194:197], v[170:173], v[108:111]
	v_mfma_f32_16x16x32_bf16 v[84:87], v[208:211], v[166:169], 0
	v_mfma_f32_16x16x32_bf16 v[84:87], v[212:215], v[170:173], v[84:87]
	v_mfma_f32_16x16x32_bf16 v[80:83], v[216:219], v[166:169], 0
	v_mfma_f32_16x16x32_bf16 v[80:83], v[220:223], v[170:173], v[80:83]
	v_mfma_f32_16x16x32_bf16 v[72:75], v[216:219], v[174:177], 0
	v_mfma_f32_16x16x32_bf16 v[72:75], v[220:223], v[178:181], v[72:75]
	v_mfma_f32_16x16x32_bf16 v[76:79], v[208:211], v[174:177], 0
	v_mfma_f32_16x16x32_bf16 v[76:79], v[212:215], v[178:181], v[76:79]
	v_mfma_f32_16x16x32_bf16 v[92:95], v[190:193], v[174:177], 0
	v_mfma_f32_16x16x32_bf16 v[92:95], v[194:197], v[178:181], v[92:95]
	v_mfma_f32_16x16x32_bf16 v[100:103], v[182:185], v[174:177], 0
	v_mfma_f32_16x16x32_bf16 v[100:103], v[186:189], v[178:181], v[100:103]
	s_barrier
	s_add_i32 s58, s58, s35
	v_lshl_add_u64 v[136:137], s[12:13], 0, v[2:3]
	s_mov_b32 m0, s58
	ds_read_b128 v[150:153], v7 offset:16384
	ds_read_b128 v[154:157], v7 offset:17408
	ds_read_b128 v[158:161], v7 offset:18432
	ds_read_b128 v[162:165], v7 offset:19456
	ds_read_b128 v[166:169], v7 offset:20480
	ds_read_b128 v[170:173], v7 offset:21504
	ds_read_b128 v[174:177], v7 offset:22528
	ds_read_b128 v[178:181], v7 offset:23552
	global_load_lds_dwordx4 v[136:137], off
	s_add_i32 m0, s58, 0x2000
	s_add_u32 s58, s12, 0x20000
	v_lshl_add_u64 v[198:199], s[12:13], 0, v[4:5]
	s_addc_u32 s59, s13, 0
	s_add_i32 s60, s60, s35
	global_load_lds_dwordx4 v[198:199], off
	v_lshl_add_u64 v[204:205], s[58:59], 0, v[2:3]
	s_mov_b32 m0, s60
	v_lshl_add_u64 v[224:225], s[14:15], 0, v[138:139]
	global_load_lds_dwordx4 v[204:205], off
	v_lshl_add_u64 v[204:205], s[58:59], 0, v[4:5]
	s_add_i32 m0, s60, 0x2000
	s_nop 0
	global_load_lds_dwordx4 v[204:205], off
	v_lshl_add_u64 v[204:205], s[14:15], 0, v[140:141]
	s_mov_b32 m0, s38
	s_nop 0
	global_load_lds_dwordx4 v[204:205], off
	s_mov_b32 m0, s39
	s_nop 0
	global_load_lds_dwordx4 v[224:225], off
	s_waitcnt vmcnt(8)
	s_waitcnt lgkmcnt(0)
	s_barrier
	s_waitcnt lgkmcnt(0)
	v_mfma_f32_16x16x32_bf16 v[68:71], v[182:185], v[150:153], 0
	v_mfma_f32_16x16x32_bf16 v[68:71], v[186:189], v[154:157], v[68:71]
	v_mfma_f32_16x16x32_bf16 v[64:67], v[190:193], v[150:153], 0
	v_mfma_f32_16x16x32_bf16 v[64:67], v[194:197], v[154:157], v[64:67]
	v_mfma_f32_16x16x32_bf16 v[48:51], v[208:211], v[150:153], 0
	v_mfma_f32_16x16x32_bf16 v[48:51], v[212:215], v[154:157], v[48:51]
	v_mfma_f32_16x16x32_bf16 v[40:43], v[216:219], v[150:153], 0
	v_mfma_f32_16x16x32_bf16 v[40:43], v[220:223], v[154:157], v[40:43]
	v_mfma_f32_16x16x32_bf16 v[24:27], v[216:219], v[158:161], 0
	v_mfma_f32_16x16x32_bf16 v[24:27], v[220:223], v[162:165], v[24:27]
	v_mfma_f32_16x16x32_bf16 v[32:35], v[208:211], v[158:161], 0
	v_mfma_f32_16x16x32_bf16 v[32:35], v[212:215], v[162:165], v[32:35]
	v_mfma_f32_16x16x32_bf16 v[56:59], v[190:193], v[158:161], 0
	v_mfma_f32_16x16x32_bf16 v[56:59], v[194:197], v[162:165], v[56:59]
	v_mfma_f32_16x16x32_bf16 v[60:63], v[182:185], v[158:161], 0
	v_mfma_f32_16x16x32_bf16 v[60:63], v[186:189], v[162:165], v[60:63]
	v_mfma_f32_16x16x32_bf16 v[52:55], v[182:185], v[166:169], 0
	v_mfma_f32_16x16x32_bf16 v[52:55], v[186:189], v[170:173], v[52:55]
	v_mfma_f32_16x16x32_bf16 v[44:47], v[190:193], v[166:169], 0
	v_mfma_f32_16x16x32_bf16 v[44:47], v[194:197], v[170:173], v[44:47]
	v_mfma_f32_16x16x32_bf16 v[20:23], v[208:211], v[166:169], 0
	v_mfma_f32_16x16x32_bf16 v[20:23], v[212:215], v[170:173], v[20:23]
	v_mfma_f32_16x16x32_bf16 v[16:19], v[216:219], v[166:169], 0
	v_mfma_f32_16x16x32_bf16 v[16:19], v[220:223], v[170:173], v[16:19]
	v_mfma_f32_16x16x32_bf16 v[8:11], v[216:219], v[174:177], 0
	v_mfma_f32_16x16x32_bf16 v[8:11], v[220:223], v[178:181], v[8:11]
	v_mfma_f32_16x16x32_bf16 v[12:15], v[208:211], v[174:177], 0
	v_mfma_f32_16x16x32_bf16 v[12:15], v[212:215], v[178:181], v[12:15]
	v_mfma_f32_16x16x32_bf16 v[28:31], v[190:193], v[174:177], 0
	v_mfma_f32_16x16x32_bf16 v[28:31], v[194:197], v[178:181], v[28:31]
	v_mfma_f32_16x16x32_bf16 v[36:39], v[182:185], v[174:177], 0
	v_mfma_f32_16x16x32_bf16 v[36:39], v[186:189], v[178:181], v[36:39]
	s_barrier
	s_add_i32 s58, 0, 0x18000
	s_add_i32 s59, 0, 0x1c000
	s_add_u32 s14, s14, 0x20000
	s_addc_u32 s15, s15, 0
	s_mov_b32 m0, s40
	v_add_u32_e32 v194, s58, v1
	v_add_u32_e32 v207, s59, v1
	v_lshl_add_u64 v[226:227], s[14:15], 0, v[140:141]
	ds_read_b128 v[150:153], v7 offset:32768
	ds_read_b128 v[154:157], v7 offset:33792
	ds_read_b128 v[158:161], v7 offset:34816
	ds_read_b128 v[162:165], v7 offset:35840
	ds_read_b128 v[166:169], v7 offset:36864
	ds_read_b128 v[170:173], v7 offset:37888
	ds_read_b128 v[174:177], v7 offset:38912
	ds_read_b128 v[178:181], v7 offset:39936
	ds_read_b128 v[182:185], v194
	ds_read_b128 v[186:189], v194 offset:1024
	ds_read_b128 v[190:193], v194 offset:2048
	ds_read_b128 v[194:197], v194 offset:3072
	ds_read_b128 v[208:211], v207
	ds_read_b128 v[212:215], v207 offset:1024
	ds_read_b128 v[216:219], v207 offset:2048
	ds_read_b128 v[220:223], v207 offset:3072
	global_load_lds_dwordx4 v[226:227], off
	v_lshl_add_u64 v[226:227], s[14:15], 0, v[138:139]
	s_mov_b32 m0, s41
	s_nop 0
	global_load_lds_dwordx4 v[226:227], off
	s_waitcnt vmcnt(8)
	s_waitcnt lgkmcnt(0)
	s_barrier
	s_waitcnt lgkmcnt(0)
	v_mfma_f32_16x16x32_bf16 v[132:135], v[182:185], v[150:153], v[132:135]
	v_mfma_f32_16x16x32_bf16 v[132:135], v[186:189], v[154:157], v[132:135]
	v_mfma_f32_16x16x32_bf16 v[128:131], v[190:193], v[150:153], v[128:131]
	v_mfma_f32_16x16x32_bf16 v[128:131], v[194:197], v[154:157], v[128:131]
	v_mfma_f32_16x16x32_bf16 v[112:115], v[208:211], v[150:153], v[112:115]
	v_mfma_f32_16x16x32_bf16 v[112:115], v[212:215], v[154:157], v[112:115]
	v_mfma_f32_16x16x32_bf16 v[104:107], v[216:219], v[150:153], v[104:107]
	v_mfma_f32_16x16x32_bf16 v[104:107], v[220:223], v[154:157], v[104:107]
	v_mfma_f32_16x16x32_bf16 v[88:91], v[216:219], v[158:161], v[88:91]
	v_mfma_f32_16x16x32_bf16 v[88:91], v[220:223], v[162:165], v[88:91]
	v_mfma_f32_16x16x32_bf16 v[96:99], v[208:211], v[158:161], v[96:99]
	v_mfma_f32_16x16x32_bf16 v[96:99], v[212:215], v[162:165], v[96:99]
	v_mfma_f32_16x16x32_bf16 v[120:123], v[190:193], v[158:161], v[120:123]
	v_mfma_f32_16x16x32_bf16 v[120:123], v[194:197], v[162:165], v[120:123]
	v_mfma_f32_16x16x32_bf16 v[124:127], v[182:185], v[158:161], v[124:127]
	v_mfma_f32_16x16x32_bf16 v[124:127], v[186:189], v[162:165], v[124:127]
	v_mfma_f32_16x16x32_bf16 v[116:119], v[182:185], v[166:169], v[116:119]
	v_mfma_f32_16x16x32_bf16 v[116:119], v[186:189], v[170:173], v[116:119]
	v_mfma_f32_16x16x32_bf16 v[108:111], v[190:193], v[166:169], v[108:111]
	v_mfma_f32_16x16x32_bf16 v[108:111], v[194:197], v[170:173], v[108:111]
	v_mfma_f32_16x16x32_bf16 v[84:87], v[208:211], v[166:169], v[84:87]
	v_mfma_f32_16x16x32_bf16 v[84:87], v[212:215], v[170:173], v[84:87]
	v_mfma_f32_16x16x32_bf16 v[80:83], v[216:219], v[166:169], v[80:83]
	v_mfma_f32_16x16x32_bf16 v[80:83], v[220:223], v[170:173], v[80:83]
	v_mfma_f32_16x16x32_bf16 v[72:75], v[216:219], v[174:177], v[72:75]
	v_mfma_f32_16x16x32_bf16 v[72:75], v[220:223], v[178:181], v[72:75]
	v_mfma_f32_16x16x32_bf16 v[76:79], v[208:211], v[174:177], v[76:79]
	v_mfma_f32_16x16x32_bf16 v[76:79], v[212:215], v[178:181], v[76:79]
	v_mfma_f32_16x16x32_bf16 v[92:95], v[190:193], v[174:177], v[92:95]
	v_mfma_f32_16x16x32_bf16 v[92:95], v[194:197], v[178:181], v[92:95]
	v_mfma_f32_16x16x32_bf16 v[100:103], v[182:185], v[174:177], v[100:103]
	v_mfma_f32_16x16x32_bf16 v[100:103], v[186:189], v[178:181], v[100:103]
	s_barrier
	s_add_i32 s14, s58, s35
	v_lshl_add_u64 v[136:137], v[136:137], 0, s[0:1]
	s_mov_b32 m0, s14
	ds_read_b128 v[150:153], v7 offset:49152
	ds_read_b128 v[154:157], v7 offset:50176
	ds_read_b128 v[158:161], v7 offset:51200
	ds_read_b128 v[162:165], v7 offset:52224
	ds_read_b128 v[166:169], v7 offset:53248
	ds_read_b128 v[170:173], v7 offset:54272
	ds_read_b128 v[174:177], v7 offset:55296
	ds_read_b128 v[178:181], v7 offset:56320
	global_load_lds_dwordx4 v[136:137], off
	s_add_i32 m0, s14, 0x2000
	s_add_u32 s12, s12, 0x20080
	v_lshl_add_u64 v[136:137], v[198:199], 0, s[0:1]
	s_addc_u32 s13, s13, 0
	s_add_i32 s14, s59, s35
	global_load_lds_dwordx4 v[136:137], off
	v_lshl_add_u64 v[136:137], s[12:13], 0, v[2:3]
	s_mov_b32 m0, s14
	s_nop 0
	global_load_lds_dwordx4 v[136:137], off
	v_lshl_add_u64 v[136:137], s[12:13], 0, v[4:5]
	s_add_i32 m0, s14, 0x2000
	s_nop 0
	global_load_lds_dwordx4 v[136:137], off
	v_lshl_add_u64 v[136:137], v[204:205], 0, s[0:1]
	s_mov_b32 m0, s49
	s_nop 0
	global_load_lds_dwordx4 v[136:137], off
	v_lshl_add_u64 v[136:137], v[224:225], 0, s[0:1]
	s_mov_b32 m0, s52
	s_nop 0
	global_load_lds_dwordx4 v[136:137], off
	s_waitcnt vmcnt(8)
	s_waitcnt lgkmcnt(0)
	s_barrier
	s_waitcnt lgkmcnt(0)
	v_mfma_f32_16x16x32_bf16 v[68:71], v[182:185], v[150:153], v[68:71]
	v_mfma_f32_16x16x32_bf16 v[68:71], v[186:189], v[154:157], v[68:71]
	v_mfma_f32_16x16x32_bf16 v[64:67], v[190:193], v[150:153], v[64:67]
	v_mfma_f32_16x16x32_bf16 v[64:67], v[194:197], v[154:157], v[64:67]
	v_mfma_f32_16x16x32_bf16 v[48:51], v[208:211], v[150:153], v[48:51]
	v_mfma_f32_16x16x32_bf16 v[48:51], v[212:215], v[154:157], v[48:51]
	v_mfma_f32_16x16x32_bf16 v[40:43], v[216:219], v[150:153], v[40:43]
	v_mfma_f32_16x16x32_bf16 v[40:43], v[220:223], v[154:157], v[40:43]
	v_mfma_f32_16x16x32_bf16 v[24:27], v[216:219], v[158:161], v[24:27]
	v_mfma_f32_16x16x32_bf16 v[24:27], v[220:223], v[162:165], v[24:27]
	v_mfma_f32_16x16x32_bf16 v[32:35], v[208:211], v[158:161], v[32:35]
	v_mfma_f32_16x16x32_bf16 v[32:35], v[212:215], v[162:165], v[32:35]
	v_mfma_f32_16x16x32_bf16 v[56:59], v[190:193], v[158:161], v[56:59]
	v_mfma_f32_16x16x32_bf16 v[56:59], v[194:197], v[162:165], v[56:59]
	v_mfma_f32_16x16x32_bf16 v[60:63], v[182:185], v[158:161], v[60:63]
	v_mfma_f32_16x16x32_bf16 v[60:63], v[186:189], v[162:165], v[60:63]
	v_mfma_f32_16x16x32_bf16 v[52:55], v[182:185], v[166:169], v[52:55]
	v_mfma_f32_16x16x32_bf16 v[52:55], v[186:189], v[170:173], v[52:55]
	v_mfma_f32_16x16x32_bf16 v[44:47], v[190:193], v[166:169], v[44:47]
	v_mfma_f32_16x16x32_bf16 v[44:47], v[194:197], v[170:173], v[44:47]
	v_mfma_f32_16x16x32_bf16 v[20:23], v[208:211], v[166:169], v[20:23]
	v_mfma_f32_16x16x32_bf16 v[20:23], v[212:215], v[170:173], v[20:23]
	v_mfma_f32_16x16x32_bf16 v[16:19], v[216:219], v[166:169], v[16:19]
	v_mfma_f32_16x16x32_bf16 v[16:19], v[220:223], v[170:173], v[16:19]
	v_mfma_f32_16x16x32_bf16 v[8:11], v[216:219], v[174:177], v[8:11]
	v_mfma_f32_16x16x32_bf16 v[8:11], v[220:223], v[178:181], v[8:11]
	v_mfma_f32_16x16x32_bf16 v[12:15], v[208:211], v[174:177], v[12:15]
	v_mfma_f32_16x16x32_bf16 v[12:15], v[212:215], v[178:181], v[12:15]
	v_mfma_f32_16x16x32_bf16 v[28:31], v[190:193], v[174:177], v[28:31]
	v_mfma_f32_16x16x32_bf16 v[28:31], v[194:197], v[178:181], v[28:31]
	v_mfma_f32_16x16x32_bf16 v[36:39], v[182:185], v[174:177], v[36:39]
	v_mfma_f32_16x16x32_bf16 v[36:39], v[186:189], v[178:181], v[36:39]
	s_barrier
	s_add_i32 s57, s57, 2
	s_add_u32 s42, s42, 0x100
	s_addc_u32 s43, s43, 0
	s_add_u32 s26, s26, 0x100
	s_addc_u32 s27, s27, 0
	s_cmp_gt_u32 s57, 5
	s_cbranch_scc0 .LBB0_620
	s_branch .Lpeelb0_exit

.LBB0_985:
	s_ashr_i32 s21, s20, 31
	s_lshl_b64 s[18:19], s[20:21], 20
	s_add_u32 s24, s22, s18
	s_addc_u32 s25, s23, s19
	s_and_b64 s[18:19], s[48:49], exec
	s_cselect_b32 s18, s25, s15
	s_cselect_b32 s19, s24, s14
	s_ashr_i32 s17, s16, 31
	s_lshl_b64 s[36:37], s[16:17], 20
	s_add_u32 s36, s26, s36
	s_addc_u32 s37, s27, s37
	s_and_b64 s[44:45], s[48:49], exec
	s_cselect_b32 s17, s37, s13
	s_cselect_b32 s21, s36, s12
	s_add_u32 s44, s14, 0x80080
	s_addc_u32 s45, s15, 0
	s_add_u32 s33, s12, 0x100
	v_mov_b32_e32 v8, 0
	s_addc_u32 s43, s13, 0
	s_mov_b32 s50, -2
	s_add_u32 s12, s44, 0xfff80080
	s_addc_u32 s13, s45, -1
	s_cmp_eq_u32 s50, 28
	s_cselect_b32 s15, s18, s13
	s_cselect_b32 s14, s19, s12
	s_cselect_b32 s13, s17, s43
	s_cselect_b32 s12, s21, s33
	s_add_i32 s51, 0, 0x10000
	v_add_u32_e32 v2, s51, v7
	s_add_i32 s63, 0, 0x14000
	ds_read_b128 v[150:153], v155
	ds_read_b128 v[156:159], v155 offset:1024
	ds_read_b128 v[160:163], v155 offset:2048
	ds_read_b128 v[164:167], v155 offset:3072
	ds_read_b128 v[168:171], v155 offset:4096
	ds_read_b128 v[172:175], v155 offset:5120
	ds_read_b128 v[176:179], v155 offset:6144
	ds_read_b128 v[180:183], v155 offset:7168
	ds_read_b128 v[184:187], v2
	ds_read_b128 v[188:191], v2 offset:1024
	ds_read_b128 v[192:195], v2 offset:2048
	ds_read_b128 v[196:199], v2 offset:3072
	v_add_u32_e32 v2, s63, v7
	v_lshl_add_u64 v[224:225], s[44:45], 0, v[146:147]
	s_add_i32 m0, s39, 0xc000
	ds_read_b128 v[208:211], v2
	ds_read_b128 v[212:215], v2 offset:1024
	ds_read_b128 v[216:219], v2 offset:2048
	ds_read_b128 v[220:223], v2 offset:3072
	global_load_lds_dwordx4 v[224:225], off
	v_lshl_add_u64 v[224:225], s[44:45], 0, v[148:149]
	s_add_i32 m0, s39, 0xe000
	s_nop 0
	global_load_lds_dwordx4 v[224:225], off
	s_waitcnt vmcnt(8)
	s_waitcnt lgkmcnt(0)
	s_barrier
	s_waitcnt lgkmcnt(0)
	v_mfma_f32_16x16x32_bf16 v[132:135], v[184:187], v[150:153], 0
	v_mfma_f32_16x16x32_bf16 v[132:135], v[188:191], v[156:159], v[132:135]
	v_mfma_f32_16x16x32_bf16 v[128:131], v[192:195], v[150:153], 0
	v_mfma_f32_16x16x32_bf16 v[128:131], v[196:199], v[156:159], v[128:131]
	v_mfma_f32_16x16x32_bf16 v[124:127], v[208:211], v[150:153], 0
	v_mfma_f32_16x16x32_bf16 v[124:127], v[212:215], v[156:159], v[124:127]
	v_mfma_f32_16x16x32_bf16 v[120:123], v[216:219], v[150:153], 0
	v_mfma_f32_16x16x32_bf16 v[120:123], v[220:223], v[156:159], v[120:123]
	v_mfma_f32_16x16x32_bf16 v[104:107], v[216:219], v[160:163], 0
	v_mfma_f32_16x16x32_bf16 v[104:107], v[220:223], v[164:167], v[104:107]
	v_mfma_f32_16x16x32_bf16 v[108:111], v[208:211], v[160:163], 0
	v_mfma_f32_16x16x32_bf16 v[108:111], v[212:215], v[164:167], v[108:111]
	v_mfma_f32_16x16x32_bf16 v[112:115], v[192:195], v[160:163], 0
	v_mfma_f32_16x16x32_bf16 v[112:115], v[196:199], v[164:167], v[112:115]
	v_mfma_f32_16x16x32_bf16 v[116:119], v[184:187], v[160:163], 0
	v_mfma_f32_16x16x32_bf16 v[116:119], v[188:191], v[164:167], v[116:119]
	v_mfma_f32_16x16x32_bf16 v[100:103], v[184:187], v[168:171], 0
	v_mfma_f32_16x16x32_bf16 v[100:103], v[188:191], v[172:175], v[100:103]
	v_mfma_f32_16x16x32_bf16 v[96:99], v[192:195], v[168:171], 0
	v_mfma_f32_16x16x32_bf16 v[96:99], v[196:199], v[172:175], v[96:99]
	v_mfma_f32_16x16x32_bf16 v[92:95], v[208:211], v[168:171], 0
	v_mfma_f32_16x16x32_bf16 v[92:95], v[212:215], v[172:175], v[92:95]
	v_mfma_f32_16x16x32_bf16 v[88:91], v[216:219], v[168:171], 0
	v_mfma_f32_16x16x32_bf16 v[88:91], v[220:223], v[172:175], v[88:91]
	v_mfma_f32_16x16x32_bf16 v[72:75], v[216:219], v[176:179], 0
	v_mfma_f32_16x16x32_bf16 v[72:75], v[220:223], v[180:183], v[72:75]
	v_mfma_f32_16x16x32_bf16 v[76:79], v[208:211], v[176:179], 0
	v_mfma_f32_16x16x32_bf16 v[76:79], v[212:215], v[180:183], v[76:79]
	v_mfma_f32_16x16x32_bf16 v[80:83], v[192:195], v[176:179], 0
	v_mfma_f32_16x16x32_bf16 v[80:83], v[196:199], v[180:183], v[80:83]
	v_mfma_f32_16x16x32_bf16 v[84:87], v[184:187], v[176:179], 0
	v_mfma_f32_16x16x32_bf16 v[84:87], v[188:191], v[180:183], v[84:87]
	s_barrier
	s_add_i32 s51, s51, s38
	v_lshl_add_u64 v[224:225], s[12:13], 0, v[138:139]
	s_mov_b32 m0, s51
	ds_read_b128 v[150:153], v155 offset:16384
	ds_read_b128 v[156:159], v155 offset:17408
	ds_read_b128 v[160:163], v155 offset:18432
	ds_read_b128 v[164:167], v155 offset:19456
	ds_read_b128 v[168:171], v155 offset:20480
	ds_read_b128 v[172:175], v155 offset:21504
	ds_read_b128 v[176:179], v155 offset:22528
	ds_read_b128 v[180:183], v155 offset:23552
	global_load_lds_dwordx4 v[224:225], off
	s_add_i32 m0, s51, 0x2000
	s_add_u32 s64, s12, 0x80000
	v_lshl_add_u64 v[226:227], s[12:13], 0, v[4:5]
	s_addc_u32 s65, s13, 0
	s_add_i32 s51, s63, s38
	global_load_lds_dwordx4 v[226:227], off
	v_lshl_add_u64 v[228:229], s[64:65], 0, v[138:139]
	s_mov_b32 m0, s51
	v_lshl_add_u64 v[230:231], s[14:15], 0, v[136:137]
	global_load_lds_dwordx4 v[228:229], off
	v_lshl_add_u64 v[228:229], s[64:65], 0, v[4:5]
	s_add_i32 m0, s51, 0x2000
	s_nop 0
	global_load_lds_dwordx4 v[228:229], off
	v_lshl_add_u64 v[228:229], s[14:15], 0, v[140:141]
	s_mov_b32 m0, s39
	s_nop 0
	global_load_lds_dwordx4 v[228:229], off
	s_mov_b32 m0, s40
	s_nop 0
	global_load_lds_dwordx4 v[230:231], off
	s_waitcnt vmcnt(8)
	s_waitcnt lgkmcnt(0)
	s_barrier
	s_waitcnt lgkmcnt(0)
	v_mfma_f32_16x16x32_bf16 v[68:71], v[184:187], v[150:153], 0
	v_mfma_f32_16x16x32_bf16 v[68:71], v[188:191], v[156:159], v[68:71]
	v_mfma_f32_16x16x32_bf16 v[64:67], v[192:195], v[150:153], 0
	v_mfma_f32_16x16x32_bf16 v[64:67], v[196:199], v[156:159], v[64:67]
	v_mfma_f32_16x16x32_bf16 v[60:63], v[208:211], v[150:153], 0
	v_mfma_f32_16x16x32_bf16 v[60:63], v[212:215], v[156:159], v[60:63]
	v_mfma_f32_16x16x32_bf16 v[56:59], v[216:219], v[150:153], 0
	v_mfma_f32_16x16x32_bf16 v[56:59], v[220:223], v[156:159], v[56:59]
	v_mfma_f32_16x16x32_bf16 v[40:43], v[216:219], v[160:163], 0
	v_mfma_f32_16x16x32_bf16 v[40:43], v[220:223], v[164:167], v[40:43]
	v_mfma_f32_16x16x32_bf16 v[44:47], v[208:211], v[160:163], 0
	v_mfma_f32_16x16x32_bf16 v[44:47], v[212:215], v[164:167], v[44:47]
	v_mfma_f32_16x16x32_bf16 v[48:51], v[192:195], v[160:163], 0
	v_mfma_f32_16x16x32_bf16 v[48:51], v[196:199], v[164:167], v[48:51]
	v_mfma_f32_16x16x32_bf16 v[52:55], v[184:187], v[160:163], 0
	v_mfma_f32_16x16x32_bf16 v[52:55], v[188:191], v[164:167], v[52:55]
	v_mfma_f32_16x16x32_bf16 v[36:39], v[184:187], v[168:171], 0
	v_mfma_f32_16x16x32_bf16 v[36:39], v[188:191], v[172:175], v[36:39]
	v_mfma_f32_16x16x32_bf16 v[32:35], v[192:195], v[168:171], 0
	v_mfma_f32_16x16x32_bf16 v[32:35], v[196:199], v[172:175], v[32:35]
	v_mfma_f32_16x16x32_bf16 v[28:31], v[208:211], v[168:171], 0
	v_mfma_f32_16x16x32_bf16 v[28:31], v[212:215], v[172:175], v[28:31]
	v_mfma_f32_16x16x32_bf16 v[24:27], v[216:219], v[168:171], 0
	v_mfma_f32_16x16x32_bf16 v[24:27], v[220:223], v[172:175], v[24:27]
	v_mfma_f32_16x16x32_bf16 v[8:11], v[216:219], v[176:179], 0
	v_mfma_f32_16x16x32_bf16 v[8:11], v[220:223], v[180:183], v[8:11]
	v_mfma_f32_16x16x32_bf16 v[12:15], v[208:211], v[176:179], 0
	v_mfma_f32_16x16x32_bf16 v[12:15], v[212:215], v[180:183], v[12:15]
	v_mfma_f32_16x16x32_bf16 v[16:19], v[192:195], v[176:179], 0
	v_mfma_f32_16x16x32_bf16 v[16:19], v[196:199], v[180:183], v[16:19]
	v_mfma_f32_16x16x32_bf16 v[20:23], v[184:187], v[176:179], 0
	v_mfma_f32_16x16x32_bf16 v[20:23], v[188:191], v[180:183], v[20:23]
	s_barrier
	s_add_i32 s51, 0, 0x18000
	s_add_i32 s63, 0, 0x1c000
	s_add_u32 s14, s14, 0x80000
	v_add_u32_e32 v2, s51, v7
	s_addc_u32 s15, s15, 0
	s_mov_b32 m0, s41
	ds_read_b128 v[150:153], v155 offset:32768
	ds_read_b128 v[156:159], v155 offset:33792
	ds_read_b128 v[160:163], v155 offset:34816
	ds_read_b128 v[164:167], v155 offset:35840
	ds_read_b128 v[168:171], v155 offset:36864
	ds_read_b128 v[172:175], v155 offset:37888
	ds_read_b128 v[176:179], v155 offset:38912
	ds_read_b128 v[180:183], v155 offset:39936
	ds_read_b128 v[184:187], v2
	ds_read_b128 v[188:191], v2 offset:1024
	ds_read_b128 v[192:195], v2 offset:2048
	ds_read_b128 v[196:199], v2 offset:3072
	v_add_u32_e32 v2, s63, v7
	v_lshl_add_u64 v[232:233], s[14:15], 0, v[140:141]
	ds_read_b128 v[208:211], v2
	ds_read_b128 v[212:215], v2 offset:1024
	ds_read_b128 v[216:219], v2 offset:2048
	ds_read_b128 v[220:223], v2 offset:3072
	global_load_lds_dwordx4 v[232:233], off
	v_lshl_add_u64 v[232:233], s[14:15], 0, v[136:137]
	s_mov_b32 m0, s47
	s_nop 0
	global_load_lds_dwordx4 v[232:233], off
	s_waitcnt vmcnt(8)
	s_waitcnt lgkmcnt(0)
	s_barrier
	s_waitcnt lgkmcnt(0)
	v_mfma_f32_16x16x32_bf16 v[132:135], v[184:187], v[150:153], v[132:135]
	v_mfma_f32_16x16x32_bf16 v[132:135], v[188:191], v[156:159], v[132:135]
	v_mfma_f32_16x16x32_bf16 v[128:131], v[192:195], v[150:153], v[128:131]
	v_mfma_f32_16x16x32_bf16 v[128:131], v[196:199], v[156:159], v[128:131]
	v_mfma_f32_16x16x32_bf16 v[124:127], v[208:211], v[150:153], v[124:127]
	v_mfma_f32_16x16x32_bf16 v[124:127], v[212:215], v[156:159], v[124:127]
	v_mfma_f32_16x16x32_bf16 v[120:123], v[216:219], v[150:153], v[120:123]
	v_mfma_f32_16x16x32_bf16 v[120:123], v[220:223], v[156:159], v[120:123]
	v_mfma_f32_16x16x32_bf16 v[104:107], v[216:219], v[160:163], v[104:107]
	v_mfma_f32_16x16x32_bf16 v[104:107], v[220:223], v[164:167], v[104:107]
	v_mfma_f32_16x16x32_bf16 v[108:111], v[208:211], v[160:163], v[108:111]
	v_mfma_f32_16x16x32_bf16 v[108:111], v[212:215], v[164:167], v[108:111]
	v_mfma_f32_16x16x32_bf16 v[112:115], v[192:195], v[160:163], v[112:115]
	v_mfma_f32_16x16x32_bf16 v[112:115], v[196:199], v[164:167], v[112:115]
	v_mfma_f32_16x16x32_bf16 v[116:119], v[184:187], v[160:163], v[116:119]
	v_mfma_f32_16x16x32_bf16 v[116:119], v[188:191], v[164:167], v[116:119]
	v_mfma_f32_16x16x32_bf16 v[100:103], v[184:187], v[168:171], v[100:103]
	v_mfma_f32_16x16x32_bf16 v[100:103], v[188:191], v[172:175], v[100:103]
	v_mfma_f32_16x16x32_bf16 v[96:99], v[192:195], v[168:171], v[96:99]
	v_mfma_f32_16x16x32_bf16 v[96:99], v[196:199], v[172:175], v[96:99]
	v_mfma_f32_16x16x32_bf16 v[92:95], v[208:211], v[168:171], v[92:95]
	v_mfma_f32_16x16x32_bf16 v[92:95], v[212:215], v[172:175], v[92:95]
	v_mfma_f32_16x16x32_bf16 v[88:91], v[216:219], v[168:171], v[88:91]
	v_mfma_f32_16x16x32_bf16 v[88:91], v[220:223], v[172:175], v[88:91]
	v_mfma_f32_16x16x32_bf16 v[72:75], v[216:219], v[176:179], v[72:75]
	v_mfma_f32_16x16x32_bf16 v[72:75], v[220:223], v[180:183], v[72:75]
	v_mfma_f32_16x16x32_bf16 v[76:79], v[208:211], v[176:179], v[76:79]
	v_mfma_f32_16x16x32_bf16 v[76:79], v[212:215], v[180:183], v[76:79]
	v_mfma_f32_16x16x32_bf16 v[80:83], v[192:195], v[176:179], v[80:83]
	v_mfma_f32_16x16x32_bf16 v[80:83], v[196:199], v[180:183], v[80:83]
	v_mfma_f32_16x16x32_bf16 v[84:87], v[184:187], v[176:179], v[84:87]
	v_mfma_f32_16x16x32_bf16 v[84:87], v[188:191], v[180:183], v[84:87]
	s_barrier
	s_add_i32 s14, s51, s38
	v_lshl_add_u64 v[224:225], v[224:225], 0, s[0:1]
	s_mov_b32 m0, s14
	ds_read_b128 v[150:153], v155 offset:49152
	ds_read_b128 v[156:159], v155 offset:50176
	ds_read_b128 v[160:163], v155 offset:51200
	ds_read_b128 v[164:167], v155 offset:52224
	ds_read_b128 v[168:171], v155 offset:53248
	ds_read_b128 v[172:175], v155 offset:54272
	ds_read_b128 v[176:179], v155 offset:55296
	ds_read_b128 v[180:183], v155 offset:56320
	global_load_lds_dwordx4 v[224:225], off
	s_add_i32 m0, s14, 0x2000
	s_add_u32 s12, s12, 0x80080
	v_lshl_add_u64 v[224:225], v[226:227], 0, s[0:1]
	s_addc_u32 s13, s13, 0
	s_add_i32 s14, s63, s38
	global_load_lds_dwordx4 v[224:225], off
	v_lshl_add_u64 v[224:225], s[12:13], 0, v[138:139]
	s_mov_b32 m0, s14
	s_nop 0
	global_load_lds_dwordx4 v[224:225], off
	v_lshl_add_u64 v[224:225], s[12:13], 0, v[4:5]
	s_add_i32 m0, s14, 0x2000
	s_nop 0
	global_load_lds_dwordx4 v[224:225], off
	v_lshl_add_u64 v[224:225], v[228:229], 0, s[0:1]
	s_mov_b32 m0, s60
	s_nop 0
	global_load_lds_dwordx4 v[224:225], off
	v_lshl_add_u64 v[224:225], v[230:231], 0, s[0:1]
	s_mov_b32 m0, s61
	s_nop 0
	global_load_lds_dwordx4 v[224:225], off
	s_waitcnt vmcnt(8)
	s_waitcnt lgkmcnt(0)
	s_barrier
	s_waitcnt lgkmcnt(0)
	v_mfma_f32_16x16x32_bf16 v[68:71], v[184:187], v[150:153], v[68:71]
	v_mfma_f32_16x16x32_bf16 v[68:71], v[188:191], v[156:159], v[68:71]
	v_mfma_f32_16x16x32_bf16 v[64:67], v[192:195], v[150:153], v[64:67]
	v_mfma_f32_16x16x32_bf16 v[64:67], v[196:199], v[156:159], v[64:67]
	v_mfma_f32_16x16x32_bf16 v[60:63], v[208:211], v[150:153], v[60:63]
	v_mfma_f32_16x16x32_bf16 v[60:63], v[212:215], v[156:159], v[60:63]
	v_mfma_f32_16x16x32_bf16 v[56:59], v[216:219], v[150:153], v[56:59]
	v_mfma_f32_16x16x32_bf16 v[56:59], v[220:223], v[156:159], v[56:59]
	v_mfma_f32_16x16x32_bf16 v[40:43], v[216:219], v[160:163], v[40:43]
	v_mfma_f32_16x16x32_bf16 v[40:43], v[220:223], v[164:167], v[40:43]
	v_mfma_f32_16x16x32_bf16 v[44:47], v[208:211], v[160:163], v[44:47]
	v_mfma_f32_16x16x32_bf16 v[44:47], v[212:215], v[164:167], v[44:47]
	v_mfma_f32_16x16x32_bf16 v[48:51], v[192:195], v[160:163], v[48:51]
	v_mfma_f32_16x16x32_bf16 v[48:51], v[196:199], v[164:167], v[48:51]
	v_mfma_f32_16x16x32_bf16 v[52:55], v[184:187], v[160:163], v[52:55]
	v_mfma_f32_16x16x32_bf16 v[52:55], v[188:191], v[164:167], v[52:55]
	v_mfma_f32_16x16x32_bf16 v[36:39], v[184:187], v[168:171], v[36:39]
	v_mfma_f32_16x16x32_bf16 v[36:39], v[188:191], v[172:175], v[36:39]
	v_mfma_f32_16x16x32_bf16 v[32:35], v[192:195], v[168:171], v[32:35]
	v_mfma_f32_16x16x32_bf16 v[32:35], v[196:199], v[172:175], v[32:35]
	v_mfma_f32_16x16x32_bf16 v[28:31], v[208:211], v[168:171], v[28:31]
	v_mfma_f32_16x16x32_bf16 v[28:31], v[212:215], v[172:175], v[28:31]
	v_mfma_f32_16x16x32_bf16 v[24:27], v[216:219], v[168:171], v[24:27]
	v_mfma_f32_16x16x32_bf16 v[24:27], v[220:223], v[172:175], v[24:27]
	v_mfma_f32_16x16x32_bf16 v[8:11], v[216:219], v[176:179], v[8:11]
	v_mfma_f32_16x16x32_bf16 v[8:11], v[220:223], v[180:183], v[8:11]
	v_mfma_f32_16x16x32_bf16 v[12:15], v[208:211], v[176:179], v[12:15]
	v_mfma_f32_16x16x32_bf16 v[12:15], v[212:215], v[180:183], v[12:15]
	v_mfma_f32_16x16x32_bf16 v[16:19], v[192:195], v[176:179], v[16:19]
	v_mfma_f32_16x16x32_bf16 v[16:19], v[196:199], v[180:183], v[16:19]
	v_mfma_f32_16x16x32_bf16 v[20:23], v[184:187], v[176:179], v[20:23]
	v_mfma_f32_16x16x32_bf16 v[20:23], v[188:191], v[180:183], v[20:23]
	s_barrier
	s_add_i32 s50, s50, 2
	s_add_u32 s44, s44, 0x100
	s_addc_u32 s45, s45, 0
	s_add_u32 s33, s33, 0x100
	s_addc_u32 s43, s43, 0
	s_cmp_gt_u32 s50, 29
	s_cbranch_scc0 .LBB0_986
	s_branch .Lpeelb1_exit

.LBB0_1481:
	s_add_u32 s50, s12, 0x100
	s_addc_u32 s51, s13, 0
	s_add_u32 s14, s26, 0x100
	v_mov_b32_e32 v8, 0
	s_addc_u32 s15, s27, 0
	s_mov_b32 s12, 0
	s_add_i32 s26, s12, 2
	s_cmp_eq_u32 s57, s12
	s_cselect_b32 s13, s43, s51
	s_cselect_b32 s12, s42, s50
	s_cselect_b32 s65, s45, s15
	s_cselect_b32 s64, s44, s14
	s_add_i32 s27, 0, 0x10000
	s_movk_i32 s66, 0xff80
	v_add_u32_e32 v121, s27, v7
	s_add_i32 s63, 0, 0x14000
	v_lshl_add_u64 v[178:179], s[50:51], 0, v[108:109]
	s_mov_b32 s67, -1
	ds_read_b128 v[110:113], v119
	ds_read_b128 v[114:117], v119 offset:1024
	ds_read_b128 v[122:125], v119 offset:2048
	ds_read_b128 v[126:129], v119 offset:3072
	ds_read_b128 v[130:133], v119 offset:4096
	ds_read_b128 v[134:137], v119 offset:5120
	ds_read_b128 v[138:141], v119 offset:6144
	ds_read_b128 v[142:145], v119 offset:7168
	ds_read_b128 v[146:149], v121
	ds_read_b128 v[150:153], v121 offset:1024
	ds_read_b128 v[154:157], v121 offset:2048
	ds_read_b128 v[158:161], v121 offset:3072
	v_add_u32_e32 v121, s63, v7
	v_lshl_add_u64 v[178:179], v[178:179], 0, s[66:67]
	s_add_i32 m0, s39, 0xc000
	ds_read_b128 v[162:165], v121
	ds_read_b128 v[166:169], v121 offset:1024
	ds_read_b128 v[170:173], v121 offset:2048
	ds_read_b128 v[174:177], v121 offset:3072
	global_load_lds_dwordx4 v[178:179], off
	s_waitcnt vmcnt(7)
	s_waitcnt lgkmcnt(0)
	s_barrier
	s_waitcnt lgkmcnt(0)
	v_mfma_f32_16x16x32_bf16 v[100:103], v[146:149], v[110:113], 0
	v_mfma_f32_16x16x32_bf16 v[100:103], v[150:153], v[114:117], v[100:103]
	v_mfma_f32_16x16x32_bf16 v[96:99], v[154:157], v[110:113], 0
	v_mfma_f32_16x16x32_bf16 v[96:99], v[158:161], v[114:117], v[96:99]
	v_mfma_f32_16x16x32_bf16 v[88:91], v[162:165], v[110:113], 0
	v_mfma_f32_16x16x32_bf16 v[88:91], v[166:169], v[114:117], v[88:91]
	v_mfma_f32_16x16x32_bf16 v[84:87], v[170:173], v[110:113], 0
	v_mfma_f32_16x16x32_bf16 v[84:87], v[174:177], v[114:117], v[84:87]
	v_mfma_f32_16x16x32_bf16 v[68:71], v[170:173], v[122:125], 0
	v_mfma_f32_16x16x32_bf16 v[68:71], v[174:177], v[126:129], v[68:71]
	v_mfma_f32_16x16x32_bf16 v[76:79], v[162:165], v[122:125], 0
	v_mfma_f32_16x16x32_bf16 v[76:79], v[166:169], v[126:129], v[76:79]
	v_mfma_f32_16x16x32_bf16 v[80:83], v[154:157], v[122:125], 0
	v_mfma_f32_16x16x32_bf16 v[80:83], v[158:161], v[126:129], v[80:83]
	v_mfma_f32_16x16x32_bf16 v[92:95], v[146:149], v[122:125], 0
	v_mfma_f32_16x16x32_bf16 v[92:95], v[150:153], v[126:129], v[92:95]
	v_mfma_f32_16x16x32_bf16 v[72:75], v[146:149], v[130:133], 0
	v_mfma_f32_16x16x32_bf16 v[72:75], v[150:153], v[134:137], v[72:75]
	v_mfma_f32_16x16x32_bf16 v[64:67], v[154:157], v[130:133], 0
	v_mfma_f32_16x16x32_bf16 v[64:67], v[158:161], v[134:137], v[64:67]
	v_mfma_f32_16x16x32_bf16 v[60:63], v[162:165], v[130:133], 0
	v_mfma_f32_16x16x32_bf16 v[60:63], v[166:169], v[134:137], v[60:63]
	v_mfma_f32_16x16x32_bf16 v[52:55], v[170:173], v[130:133], 0
	v_mfma_f32_16x16x32_bf16 v[52:55], v[174:177], v[134:137], v[52:55]
	v_mfma_f32_16x16x32_bf16 v[40:43], v[170:173], v[138:141], 0
	v_mfma_f32_16x16x32_bf16 v[40:43], v[174:177], v[142:145], v[40:43]
	v_mfma_f32_16x16x32_bf16 v[44:47], v[162:165], v[138:141], 0
	v_mfma_f32_16x16x32_bf16 v[44:47], v[166:169], v[142:145], v[44:47]
	v_mfma_f32_16x16x32_bf16 v[48:51], v[154:157], v[138:141], 0
	v_mfma_f32_16x16x32_bf16 v[48:51], v[158:161], v[142:145], v[48:51]
	v_mfma_f32_16x16x32_bf16 v[56:59], v[146:149], v[138:141], 0
	v_mfma_f32_16x16x32_bf16 v[56:59], v[150:153], v[142:145], v[56:59]
	s_barrier
	s_add_i32 s27, s27, s22
	v_lshl_add_u64 v[178:179], s[64:65], 0, v[2:3]
	s_mov_b32 m0, s27
	ds_read_b128 v[110:113], v120 offset:16384
	ds_read_b128 v[114:117], v120 offset:17408
	ds_read_b128 v[122:125], v120 offset:18432
	ds_read_b128 v[126:129], v120 offset:19456
	global_load_lds_dwordx4 v[178:179], off
	s_add_i32 m0, s27, 0x2000
	v_lshl_add_u64 v[180:181], s[64:65], 0, v[4:5]
	s_add_u32 s64, s64, s90
	s_addc_u32 s65, s65, 0
	s_add_i32 s27, s63, s22
	global_load_lds_dwordx4 v[180:181], off
	v_lshl_add_u64 v[182:183], s[64:65], 0, v[2:3]
	s_mov_b32 m0, s27
	v_lshl_add_u64 v[184:185], s[64:65], 0, v[4:5]
	global_load_lds_dwordx4 v[182:183], off
	s_add_i32 m0, s27, 0x2000
	v_lshl_add_u64 v[186:187], s[12:13], 0, v[106:107]
	global_load_lds_dwordx4 v[184:185], off
	s_mov_b32 m0, s39
	v_lshl_add_u64 v[188:189], s[12:13], 0, v[104:105]
	global_load_lds_dwordx4 v[186:187], off
	s_mov_b32 m0, s40
	s_nop 0
	global_load_lds_dwordx4 v[188:189], off
	s_waitcnt vmcnt(7)
	s_waitcnt lgkmcnt(0)
	s_barrier
	s_waitcnt lgkmcnt(0)
	v_mfma_f32_16x16x32_bf16 v[36:39], v[146:149], v[110:113], 0
	v_mfma_f32_16x16x32_bf16 v[36:39], v[150:153], v[114:117], v[36:39]
	v_mfma_f32_16x16x32_bf16 v[32:35], v[154:157], v[110:113], 0
	v_mfma_f32_16x16x32_bf16 v[32:35], v[158:161], v[114:117], v[32:35]
	v_mfma_f32_16x16x32_bf16 v[28:31], v[162:165], v[110:113], 0
	v_mfma_f32_16x16x32_bf16 v[28:31], v[166:169], v[114:117], v[28:31]
	v_mfma_f32_16x16x32_bf16 v[24:27], v[170:173], v[110:113], 0
	v_mfma_f32_16x16x32_bf16 v[24:27], v[174:177], v[114:117], v[24:27]
	v_mfma_f32_16x16x32_bf16 v[20:23], v[146:149], v[122:125], 0
	v_mfma_f32_16x16x32_bf16 v[20:23], v[150:153], v[126:129], v[20:23]
	v_mfma_f32_16x16x32_bf16 v[16:19], v[154:157], v[122:125], 0
	v_mfma_f32_16x16x32_bf16 v[16:19], v[158:161], v[126:129], v[16:19]
	v_mfma_f32_16x16x32_bf16 v[12:15], v[162:165], v[122:125], 0
	v_mfma_f32_16x16x32_bf16 v[12:15], v[166:169], v[126:129], v[12:15]
	v_mfma_f32_16x16x32_bf16 v[8:11], v[170:173], v[122:125], 0
	v_mfma_f32_16x16x32_bf16 v[8:11], v[174:177], v[126:129], v[8:11]
	s_barrier
	s_add_i32 s27, 0, 0x18000
	s_add_i32 s63, 0, 0x1c000
	s_add_u32 s12, s12, s90
	v_add_u32_e32 v121, s27, v7
	s_addc_u32 s13, s13, 0
	ds_read_b128 v[110:113], v119 offset:32768
	ds_read_b128 v[114:117], v119 offset:33792
	ds_read_b128 v[122:125], v119 offset:34816
	ds_read_b128 v[126:129], v119 offset:35840
	ds_read_b128 v[130:133], v119 offset:36864
	ds_read_b128 v[134:137], v119 offset:37888
	ds_read_b128 v[138:141], v119 offset:38912
	ds_read_b128 v[142:145], v119 offset:39936
	ds_read_b128 v[146:149], v121
	ds_read_b128 v[150:153], v121 offset:1024
	ds_read_b128 v[154:157], v121 offset:2048
	ds_read_b128 v[158:161], v121 offset:3072
	v_add_u32_e32 v121, s63, v7
	v_lshl_add_u64 v[190:191], s[12:13], 0, v[106:107]
	s_mov_b32 m0, s41
	ds_read_b128 v[162:165], v121
	ds_read_b128 v[166:169], v121 offset:1024
	ds_read_b128 v[170:173], v121 offset:2048
	ds_read_b128 v[174:177], v121 offset:3072
	global_load_lds_dwordx4 v[190:191], off
	s_waitcnt vmcnt(7)
	s_waitcnt lgkmcnt(0)
	s_barrier
	s_waitcnt lgkmcnt(0)
	v_mfma_f32_16x16x32_bf16 v[100:103], v[146:149], v[110:113], v[100:103]
	v_mfma_f32_16x16x32_bf16 v[100:103], v[150:153], v[114:117], v[100:103]
	v_mfma_f32_16x16x32_bf16 v[96:99], v[154:157], v[110:113], v[96:99]
	v_mfma_f32_16x16x32_bf16 v[96:99], v[158:161], v[114:117], v[96:99]
	v_mfma_f32_16x16x32_bf16 v[88:91], v[162:165], v[110:113], v[88:91]
	v_mfma_f32_16x16x32_bf16 v[88:91], v[166:169], v[114:117], v[88:91]
	v_mfma_f32_16x16x32_bf16 v[84:87], v[170:173], v[110:113], v[84:87]
	v_mfma_f32_16x16x32_bf16 v[84:87], v[174:177], v[114:117], v[84:87]
	v_mfma_f32_16x16x32_bf16 v[68:71], v[170:173], v[122:125], v[68:71]
	v_mfma_f32_16x16x32_bf16 v[68:71], v[174:177], v[126:129], v[68:71]
	v_mfma_f32_16x16x32_bf16 v[76:79], v[162:165], v[122:125], v[76:79]
	v_mfma_f32_16x16x32_bf16 v[76:79], v[166:169], v[126:129], v[76:79]
	v_mfma_f32_16x16x32_bf16 v[80:83], v[154:157], v[122:125], v[80:83]
	v_mfma_f32_16x16x32_bf16 v[80:83], v[158:161], v[126:129], v[80:83]
	v_mfma_f32_16x16x32_bf16 v[92:95], v[146:149], v[122:125], v[92:95]
	v_mfma_f32_16x16x32_bf16 v[92:95], v[150:153], v[126:129], v[92:95]
	v_mfma_f32_16x16x32_bf16 v[72:75], v[146:149], v[130:133], v[72:75]
	v_mfma_f32_16x16x32_bf16 v[72:75], v[150:153], v[134:137], v[72:75]
	v_mfma_f32_16x16x32_bf16 v[64:67], v[154:157], v[130:133], v[64:67]
	v_mfma_f32_16x16x32_bf16 v[64:67], v[158:161], v[134:137], v[64:67]
	v_mfma_f32_16x16x32_bf16 v[60:63], v[162:165], v[130:133], v[60:63]
	v_mfma_f32_16x16x32_bf16 v[60:63], v[166:169], v[134:137], v[60:63]
	v_mfma_f32_16x16x32_bf16 v[52:55], v[170:173], v[130:133], v[52:55]
	v_mfma_f32_16x16x32_bf16 v[52:55], v[174:177], v[134:137], v[52:55]
	v_mfma_f32_16x16x32_bf16 v[40:43], v[170:173], v[138:141], v[40:43]
	v_mfma_f32_16x16x32_bf16 v[40:43], v[174:177], v[142:145], v[40:43]
	v_mfma_f32_16x16x32_bf16 v[44:47], v[162:165], v[138:141], v[44:47]
	v_mfma_f32_16x16x32_bf16 v[44:47], v[166:169], v[142:145], v[44:47]
	v_mfma_f32_16x16x32_bf16 v[48:51], v[154:157], v[138:141], v[48:51]
	v_mfma_f32_16x16x32_bf16 v[48:51], v[158:161], v[142:145], v[48:51]
	v_mfma_f32_16x16x32_bf16 v[56:59], v[146:149], v[138:141], v[56:59]
	v_mfma_f32_16x16x32_bf16 v[56:59], v[150:153], v[142:145], v[56:59]
	s_barrier
	s_add_i32 s12, s27, s22
	v_lshl_add_u64 v[130:131], v[178:179], 0, s[0:1]
	s_mov_b32 m0, s12
	ds_read_b128 v[110:113], v120 offset:49152
	ds_read_b128 v[114:117], v120 offset:50176
	ds_read_b128 v[122:125], v120 offset:51200
	ds_read_b128 v[126:129], v120 offset:52224
	global_load_lds_dwordx4 v[130:131], off
	v_lshl_add_u64 v[130:131], v[180:181], 0, s[0:1]
	s_add_i32 m0, s12, 0x2000
	s_add_i32 s12, s63, s22
	global_load_lds_dwordx4 v[130:131], off
	v_lshl_add_u64 v[130:131], v[182:183], 0, s[0:1]
	s_mov_b32 m0, s12
	s_nop 0
	global_load_lds_dwordx4 v[130:131], off
	v_lshl_add_u64 v[130:131], v[184:185], 0, s[0:1]
	s_add_i32 m0, s12, 0x2000
	s_nop 0
	global_load_lds_dwordx4 v[130:131], off
	v_lshl_add_u64 v[130:131], v[186:187], 0, s[0:1]
	s_mov_b32 m0, s53
	s_nop 0
	global_load_lds_dwordx4 v[130:131], off
	v_lshl_add_u64 v[130:131], v[188:189], 0, s[0:1]
	s_mov_b32 m0, s54
	s_nop 0
	global_load_lds_dwordx4 v[130:131], off
	s_waitcnt vmcnt(7)
	s_waitcnt lgkmcnt(0)
	s_barrier
	s_waitcnt lgkmcnt(0)
	v_mfma_f32_16x16x32_bf16 v[36:39], v[146:149], v[110:113], v[36:39]
	v_mfma_f32_16x16x32_bf16 v[36:39], v[150:153], v[114:117], v[36:39]
	v_mfma_f32_16x16x32_bf16 v[32:35], v[154:157], v[110:113], v[32:35]
	v_mfma_f32_16x16x32_bf16 v[32:35], v[158:161], v[114:117], v[32:35]
	v_mfma_f32_16x16x32_bf16 v[28:31], v[162:165], v[110:113], v[28:31]
	v_mfma_f32_16x16x32_bf16 v[28:31], v[166:169], v[114:117], v[28:31]
	v_mfma_f32_16x16x32_bf16 v[24:27], v[170:173], v[110:113], v[24:27]
	v_mfma_f32_16x16x32_bf16 v[24:27], v[174:177], v[114:117], v[24:27]
	v_mfma_f32_16x16x32_bf16 v[20:23], v[146:149], v[122:125], v[20:23]
	v_mfma_f32_16x16x32_bf16 v[20:23], v[150:153], v[126:129], v[20:23]
	v_mfma_f32_16x16x32_bf16 v[16:19], v[154:157], v[122:125], v[16:19]
	v_mfma_f32_16x16x32_bf16 v[16:19], v[158:161], v[126:129], v[16:19]
	v_mfma_f32_16x16x32_bf16 v[12:15], v[162:165], v[122:125], v[12:15]
	v_mfma_f32_16x16x32_bf16 v[12:15], v[166:169], v[126:129], v[12:15]
	v_mfma_f32_16x16x32_bf16 v[8:11], v[170:173], v[122:125], v[8:11]
	v_mfma_f32_16x16x32_bf16 v[8:11], v[174:177], v[126:129], v[8:11]
	s_barrier
	s_add_u32 s50, s50, 0x100
	s_addc_u32 s51, s51, 0
	s_add_u32 s14, s14, 0x100
	s_addc_u32 s15, s15, 0
	s_cmp_ge_u32 s26, s55
	s_mov_b32 s12, s26
	s_cbranch_scc0 .LBB0_1482
	s_branch .Lpeelb2_exit
